# v38: v36 + write-through (sc1) stores for the weight conversions that run on light workgroups in P1/P3/P9
# baseline (speedup 1.0000x reference)
; #define LAS __attribute__((address_space(3)))
; __device__ __forceinline__ unsigned cvtpk(float lo, float hi) { f32x2_t v = {lo, hi}; bf16x2_t b = __builtin_convertvector(v, bf16x2_t); return __builtin_bit_cast(unsigned, b); }
; #define LDS_WAIT() asm volatile("s_waitcnt lgkmcnt(0)" ::: "memory")
; __device__ __forceinline__ void conv_emit(const ConvJob& j, int lane, const ConvSet& s, LAS float* scr) {
;     const int k0 = 64 * j.kb; int cnt; (void)vgroup_src(j.kind, j.g, cnt);
;     const int ks = lane >> 3, n4 = (lane & 7) * 4, c = lane & 7; const bool okc = n4 < cnt;
;     const f32x4 one = (f32x4){1.f, 1.f, 1.f, 1.f}; const f32x4 g0 = j.gain ? s.g0 : one, g1 = j.gain ? s.g1 : one;
; #pragma unroll
;     for (int i = 0; i < 8; ++i) { LAS float* sp = scr + (8 * i + ks) * 33 + n4;
; #pragma unroll
;         for (int e = 0; e < 4; ++e) sp[e] = okc ? s.v[i][e] : 0.f; }
;     LDS_WAIT(); asm volatile("" ::: "memory");
; #pragma unroll
;     for (int q = 0; q < 4; ++q) { const int nn = (lane >> 3) + 8 * q; const LAS float* sr = scr + (8 * c) * 33 + nn;
;         u32x4 o; o.x = cvtpk(sr[0 * 33] * g0[0], sr[1 * 33] * g0[1]); o.y = cvtpk(sr[2 * 33] * g0[2], sr[3 * 33] * g0[3]); o.z = cvtpk(sr[4 * 33] * g1[0], sr[5 * 33] * g1[1]); o.w = cvtpk(sr[6 * 33] * g1[2], sr[7 * 33] * g1[3]);
.LBB0_429:
	s_cmpk_lt_i32 s24, 0xd0
	s_cselect_b64 s[20:21], -1, 0
	s_and_b32 s29, s24, 7
	s_cmp_eq_u32 s29, 0
	s_cselect_b32 s29, 16, 0
	s_or_b64 s[18:19], s[18:19], s[20:21]
	s_and_b64 s[18:19], s[18:19], exec
	s_cselect_b32 s18, 32, s29
	v_cmp_gt_u32_e32 vcc, s18, v126
	s_waitcnt vmcnt(32)
	v_cndmask_b32_e64 v89, v89, 1.0, s[8:9]
	v_cndmask_b32_e64 v88, v88, 1.0, s[8:9]
	s_waitcnt vmcnt(31)
	v_cndmask_b32_e32 v118, 0, v118, vcc
	v_cndmask_b32_e32 v119, 0, v119, vcc
	s_waitcnt vmcnt(30)
	v_cndmask_b32_e32 v114, 0, v114, vcc
	v_cndmask_b32_e32 v115, 0, v115, vcc
	s_waitcnt vmcnt(29)
	v_cndmask_b32_e32 v110, 0, v110, vcc
	v_cndmask_b32_e32 v111, 0, v111, vcc
	s_waitcnt vmcnt(28)
	v_cndmask_b32_e32 v106, 0, v106, vcc
	v_cndmask_b32_e32 v107, 0, v107, vcc
	s_waitcnt vmcnt(27)
	v_cndmask_b32_e32 v102, 0, v102, vcc
	v_cndmask_b32_e32 v103, 0, v103, vcc
	s_waitcnt vmcnt(26)
	v_cndmask_b32_e32 v98, 0, v98, vcc
	v_cndmask_b32_e32 v99, 0, v99, vcc
	s_waitcnt vmcnt(25)
	v_cndmask_b32_e32 v94, 0, v94, vcc
	v_cndmask_b32_e32 v95, 0, v95, vcc
	s_waitcnt vmcnt(24)
	v_cndmask_b32_e32 v90, 0, v90, vcc
	v_cndmask_b32_e32 v91, 0, v91, vcc
	ds_write2_b32 v133, v118, v119 offset1:1
	v_cndmask_b32_e32 v118, 0, v120, vcc
	v_cndmask_b32_e32 v119, 0, v121, vcc
	ds_write2_b32 v134, v114, v115 offset1:1
	v_cndmask_b32_e32 v114, 0, v116, vcc
	v_cndmask_b32_e32 v115, 0, v117, vcc
	ds_write2_b32 v136, v110, v111 offset1:1
	v_cndmask_b32_e32 v110, 0, v112, vcc
	v_cndmask_b32_e32 v111, 0, v113, vcc
	ds_write2_b32 v138, v106, v107 offset1:1
	v_cndmask_b32_e32 v106, 0, v108, vcc
	v_cndmask_b32_e32 v107, 0, v109, vcc
	ds_write2_b32 v140, v102, v103 offset1:1
	v_cndmask_b32_e32 v102, 0, v104, vcc
	v_cndmask_b32_e32 v103, 0, v105, vcc
	ds_write2_b32 v142, v98, v99 offset1:1
	v_cndmask_b32_e32 v98, 0, v100, vcc
	v_cndmask_b32_e32 v99, 0, v101, vcc
	ds_write2_b32 v144, v94, v95 offset1:1
	v_cndmask_b32_e32 v94, 0, v96, vcc
	v_cndmask_b32_e32 v95, 0, v97, vcc
	ds_write2_b32 v146, v90, v91 offset1:1
	v_cndmask_b32_e32 v90, 0, v92, vcc
	v_cndmask_b32_e32 v91, 0, v93, vcc
	ds_write2_b32 v133, v118, v119 offset0:2 offset1:3
	ds_write2_b32 v135, v114, v115 offset1:1
	ds_write2_b32 v137, v110, v111 offset1:1
	ds_write2_b32 v139, v106, v107 offset1:1
	ds_write2_b32 v141, v102, v103 offset1:1
	ds_write2_b32 v143, v98, v99 offset1:1
	ds_write2_b32 v145, v94, v95 offset1:1
	ds_write2_b32 v147, v90, v91 offset1:1
	s_waitcnt lgkmcnt(0)
	ds_read2_b32 v[92:93], v132 offset1:8
	ds_read2_b32 v[96:97], v132 offset0:33 offset1:41
	ds_read2_b32 v[98:99], v132 offset0:66 offset1:74
	ds_read2_b32 v[100:101], v132 offset0:99 offset1:107
	ds_read2_b32 v[102:103], v132 offset0:132 offset1:140
	ds_read2_b32 v[104:105], v132 offset0:165 offset1:173
	ds_read2_b32 v[106:107], v132 offset0:198 offset1:206
	ds_read2_b32 v[108:109], v132 offset0:231 offset1:239
	v_cndmask_b32_e64 v87, v87, 1.0, s[8:9]
	v_cndmask_b32_e64 v86, v86, 1.0, s[8:9]
	v_cndmask_b32_e64 v91, v85, 1.0, s[8:9]
	v_cndmask_b32_e64 v90, v84, 1.0, s[8:9]
	v_cndmask_b32_e64 v95, v83, 1.0, s[8:9]
	v_cndmask_b32_e64 v94, v82, 1.0, s[8:9]
	s_waitcnt lgkmcnt(7)
	v_mov_b32_e32 v82, v92
	s_waitcnt lgkmcnt(6)
	v_mov_b32_e32 v83, v96
	s_waitcnt lgkmcnt(5)
	v_mov_b32_e32 v84, v98
	s_waitcnt lgkmcnt(4)
	v_mov_b32_e32 v85, v100
	v_pk_mul_f32 v[82:83], v[86:87], v[82:83]
	v_pk_mul_f32 v[84:85], v[88:89], v[84:85]
	v_cvt_pk_bf16_f32 v82, v82, v83
	v_cvt_pk_bf16_f32 v83, v84, v85
	s_waitcnt lgkmcnt(3)
	v_mov_b32_e32 v84, v102
	s_waitcnt lgkmcnt(2)
	v_mov_b32_e32 v85, v104
	s_waitcnt lgkmcnt(1)
	v_mov_b32_e32 v110, v106
	s_waitcnt lgkmcnt(0)
; #define LAS __attribute__((address_space(3)))
; __device__ __forceinline__ unsigned cvtpk(float lo, float hi) { f32x2_t v = {lo, hi}; bf16x2_t b = __builtin_convertvector(v, bf16x2_t); return __builtin_bit_cast(unsigned, b); }
; #define LDS_WAIT() asm volatile("s_waitcnt lgkmcnt(0)" ::: "memory")
; __device__ __forceinline__ void conv_emit(const ConvJob& j, int lane, const ConvSet& s, LAS float* scr) {
;     ...
;     for (int q = 0; q < 4; ++q) { const int nn = (lane >> 3) + 8 * q; const LAS float* sr = scr + (8 * c) * 33 + nn;
;         u32x4 o; o.x = cvtpk(sr[0 * 33] * g0[0], sr[1 * 33] * g0[1]); o.y = cvtpk(sr[2 * 33] * g0[2], sr[3 * 33] * g0[3]); o.z = cvtpk(sr[4 * 33] * g1[0], sr[5 * 33] * g1[1]); o.w = cvtpk(sr[6 * 33] * g1[2], sr[7 * 33] * g1[3]);
;         *(u32x4*)(j.WT + (size_t)(j.g * 32 + nn) * j.K + k0 + 8 * c) = o; }
;     LDS_WAIT(); asm volatile("" ::: "memory");
	v_mov_b32_e32 v111, v108
	s_lshl_b32 s20, s24, 5
	v_pk_mul_f32 v[84:85], v[94:95], v[84:85]
	v_pk_mul_f32 v[110:111], v[90:91], v[110:111]
	v_or_b32_e32 v92, s20, v127
	s_ashr_i32 s8, s20, 31
	s_lshl_b32 s18, s28, 6
	v_cvt_pk_bf16_f32 v84, v84, v85
	v_cvt_pk_bf16_f32 v85, v110, v111
	s_mul_i32 s21, s4, s8
	v_mul_lo_u32 v96, s5, v92
	v_mad_u64_u32 v[110:111], s[8:9], s4, v92, 0
	s_ashr_i32 s19, s18, 31
	v_add3_u32 v111, v111, s21, v96
	v_lshl_add_u64 v[110:111], v[110:111], 1, s[6:7]
	s_lshl_b64 s[8:9], s[18:19], 1
	v_lshl_add_u64 v[110:111], v[110:111], 0, s[8:9]
	v_mov_b32_e32 v125, v123
	v_lshl_add_u64 v[110:111], v[110:111], 0, v[124:125]
	v_mov_b32_e32 v96, v93
	v_mov_b32_e32 v100, v99
	global_store_dwordx4 v[110:111], v[82:85], off sc1
	v_mov_b32_e32 v104, v103
	v_mov_b32_e32 v108, v107
	v_pk_mul_f32 v[82:83], v[86:87], v[96:97]
	v_pk_mul_f32 v[84:85], v[88:89], v[100:101]
	v_cvt_pk_bf16_f32 v82, v82, v83
	v_cvt_pk_bf16_f32 v83, v84, v85
	v_pk_mul_f32 v[84:85], v[94:95], v[104:105]
	v_pk_mul_f32 v[92:93], v[90:91], v[108:109]
	v_cvt_pk_bf16_f32 v84, v84, v85
	v_cvt_pk_bf16_f32 v85, v92, v93
	v_or_b32_e32 v92, s20, v129
	v_mul_lo_u32 v96, s5, v92
	v_mad_u64_u32 v[92:93], s[18:19], s4, v92, 0
	v_add3_u32 v93, v93, s21, v96
	v_lshl_add_u64 v[92:93], v[92:93], 1, s[6:7]
	v_lshl_add_u64 v[92:93], v[92:93], 0, s[8:9]
	v_lshl_add_u64 v[92:93], v[92:93], 0, v[124:125]
	ds_read2_b32 v[96:97], v132 offset0:16 offset1:24
	ds_read2_b32 v[98:99], v132 offset0:49 offset1:57
	global_store_dwordx4 v[92:93], v[82:85], off sc1
	ds_read2_b32 v[92:93], v132 offset0:82 offset1:90
	ds_read2_b32 v[100:101], v132 offset0:115 offset1:123
	ds_read2_b32 v[102:103], v132 offset0:148 offset1:156
	ds_read2_b32 v[104:105], v132 offset0:181 offset1:189
	ds_read2_b32 v[106:107], v132 offset0:214 offset1:222
	ds_read2_b32 v[108:109], v132 offset0:247 offset1:255
	s_waitcnt lgkmcnt(7)
	v_mov_b32_e32 v82, v96
	s_waitcnt lgkmcnt(6)
	v_mov_b32_e32 v83, v98
	s_waitcnt lgkmcnt(5)
	v_mov_b32_e32 v84, v92
	s_waitcnt lgkmcnt(4)
	v_mov_b32_e32 v85, v100
	v_pk_mul_f32 v[82:83], v[86:87], v[82:83]
	v_pk_mul_f32 v[84:85], v[88:89], v[84:85]
	v_cvt_pk_bf16_f32 v82, v82, v83
	v_cvt_pk_bf16_f32 v83, v84, v85
	s_waitcnt lgkmcnt(3)
	v_mov_b32_e32 v84, v102
	s_waitcnt lgkmcnt(2)
	v_mov_b32_e32 v85, v104
	s_waitcnt lgkmcnt(1)
	v_mov_b32_e32 v110, v106
	s_waitcnt lgkmcnt(0)
	v_mov_b32_e32 v111, v108
	v_pk_mul_f32 v[84:85], v[94:95], v[84:85]
	v_pk_mul_f32 v[110:111], v[90:91], v[110:111]
	v_or_b32_e32 v92, s20, v130
	v_cvt_pk_bf16_f32 v84, v84, v85
	v_cvt_pk_bf16_f32 v85, v110, v111
	v_mul_lo_u32 v96, s5, v92
	v_mad_u64_u32 v[110:111], s[18:19], s4, v92, 0
	v_add3_u32 v111, v111, s21, v96
	v_lshl_add_u64 v[110:111], v[110:111], 1, s[6:7]
	v_lshl_add_u64 v[110:111], v[110:111], 0, s[8:9]
	v_lshl_add_u64 v[110:111], v[110:111], 0, v[124:125]
	v_mov_b32_e32 v98, v97
	v_mov_b32_e32 v100, v93
	global_store_dwordx4 v[110:111], v[82:85], off sc1
	v_mov_b32_e32 v104, v103
	v_mov_b32_e32 v108, v107
	v_pk_mul_f32 v[82:83], v[86:87], v[98:99]
	v_pk_mul_f32 v[84:85], v[88:89], v[100:101]
	v_cvt_pk_bf16_f32 v82, v82, v83
	v_cvt_pk_bf16_f32 v83, v84, v85
	v_pk_mul_f32 v[84:85], v[94:95], v[104:105]
	v_pk_mul_f32 v[86:87], v[90:91], v[108:109]
	v_cvt_pk_bf16_f32 v84, v84, v85
	v_cvt_pk_bf16_f32 v85, v86, v87
	v_or_b32_e32 v86, s20, v131
	v_mul_lo_u32 v88, s5, v86
	v_mad_u64_u32 v[86:87], s[4:5], s4, v86, 0
	v_add3_u32 v87, v87, s21, v88
	v_lshl_add_u64 v[86:87], v[86:87], 1, s[6:7]
	v_lshl_add_u64 v[86:87], v[86:87], 0, s[8:9]
	v_lshl_add_u64 v[86:87], v[86:87], 0, v[124:125]
	global_store_dwordx4 v[86:87], v[82:85], off sc1
	s_waitcnt lgkmcnt(0)

; #define LAS __attribute__((address_space(3)))
; __device__ __forceinline__ unsigned cvtpk(float lo, float hi) { f32x2_t v = {lo, hi}; bf16x2_t b = __builtin_convertvector(v, bf16x2_t); return __builtin_bit_cast(unsigned, b); }
; #define LDS_WAIT() asm volatile("s_waitcnt lgkmcnt(0)" ::: "memory")
; __device__ __forceinline__ void conv_emit(const ConvJob& j, int lane, const ConvSet& s, LAS float* scr) {
;     ...
;     for (int i = 0; i < 8; ++i) { LAS float* sp = scr + (8 * i + ks) * 33 + n4;
; #pragma unroll
;         for (int e = 0; e < 4; ++e) sp[e] = okc ? s.v[i][e] : 0.f; }
;     LDS_WAIT(); asm volatile("" ::: "memory");
; #pragma unroll
;     for (int q = 0; q < 4; ++q) { const int nn = (lane >> 3) + 8 * q; const LAS float* sr = scr + (8 * c) * 33 + nn;
;         u32x4 o; o.x = cvtpk(sr[0 * 33] * g0[0], sr[1 * 33] * g0[1]); o.y = cvtpk(sr[2 * 33] * g0[2], sr[3 * 33] * g0[3]); o.z = cvtpk(sr[4 * 33] * g1[0], sr[5 * 33] * g1[1]); o.w = cvtpk(sr[6 * 33] * g1[2], sr[7 * 33] * g1[3]);
.LBB0_458:
	s_cmpk_lt_i32 s72, 0xd0
	s_cselect_b64 s[28:29], -1, 0
	s_and_b32 s74, s72, 7
	s_cmp_eq_u32 s74, 0
	s_cselect_b32 s74, 16, 0
	s_or_b64 s[20:21], s[20:21], s[28:29]
	s_and_b64 s[20:21], s[20:21], exec
	s_cselect_b32 s20, 32, s74
	v_cmp_gt_u32_e32 vcc, s20, v126
	v_add_u32_e32 v134, 0x420, v133
	v_add_u32_e32 v136, 0x840, v133
	s_waitcnt vmcnt(27)
	v_cndmask_b32_e32 v38, 0, v38, vcc
	v_cndmask_b32_e32 v39, 0, v39, vcc
	s_waitcnt vmcnt(26)
	v_cndmask_b32_e32 v34, 0, v34, vcc
	v_cndmask_b32_e32 v35, 0, v35, vcc
	s_waitcnt vmcnt(25)
	v_cndmask_b32_e32 v30, 0, v30, vcc
	v_cndmask_b32_e32 v31, 0, v31, vcc
	s_waitcnt vmcnt(24)
	v_cndmask_b32_e32 v26, 0, v26, vcc
	v_add_u32_e32 v138, 0xc60, v133
	v_cndmask_b32_e32 v27, 0, v27, vcc
	s_waitcnt vmcnt(23)
	v_cndmask_b32_e32 v22, 0, v22, vcc
	v_add_u32_e32 v140, 0x1080, v133
	v_cndmask_b32_e32 v23, 0, v23, vcc
	s_waitcnt vmcnt(22)
	v_cndmask_b32_e32 v18, 0, v18, vcc
	v_add_u32_e32 v142, 0x14a0, v133
	v_cndmask_b32_e32 v19, 0, v19, vcc
	s_waitcnt vmcnt(21)
	v_cndmask_b32_e32 v14, 0, v14, vcc
	v_add_u32_e32 v144, 0x18c0, v133
	v_cndmask_b32_e32 v15, 0, v15, vcc
	s_waitcnt vmcnt(20)
	v_cndmask_b32_e32 v10, 0, v10, vcc
	v_add_u32_e32 v146, 0x1ce0, v133
	v_cndmask_b32_e32 v11, 0, v11, vcc
	ds_write2_b32 v133, v38, v39 offset1:1
	v_cndmask_b32_e32 v38, 0, v40, vcc
	v_cndmask_b32_e32 v39, 0, v41, vcc
	ds_write2_b32 v134, v34, v35 offset1:1
	v_cndmask_b32_e32 v34, 0, v36, vcc
	v_add_u32_e32 v135, 0x428, v133
	v_cndmask_b32_e32 v35, 0, v37, vcc
	ds_write2_b32 v136, v30, v31 offset1:1
	v_cndmask_b32_e32 v30, 0, v32, vcc
	v_add_u32_e32 v137, 0x848, v133
	v_cndmask_b32_e32 v31, 0, v33, vcc
	ds_write2_b32 v138, v26, v27 offset1:1
	v_cndmask_b32_e32 v26, 0, v28, vcc
	v_add_u32_e32 v139, 0xc68, v133
	v_cndmask_b32_e32 v27, 0, v29, vcc
	ds_write2_b32 v140, v22, v23 offset1:1
	v_cndmask_b32_e32 v22, 0, v24, vcc
	v_add_u32_e32 v141, 0x1088, v133
	v_cndmask_b32_e32 v23, 0, v25, vcc
	ds_write2_b32 v142, v18, v19 offset1:1
	v_cndmask_b32_e32 v18, 0, v20, vcc
	v_add_u32_e32 v143, 0x14a8, v133
	v_cndmask_b32_e32 v19, 0, v21, vcc
	ds_write2_b32 v144, v14, v15 offset1:1
	v_cndmask_b32_e32 v14, 0, v16, vcc
	v_add_u32_e32 v145, 0x18c8, v133
	v_cndmask_b32_e32 v15, 0, v17, vcc
	ds_write2_b32 v146, v10, v11 offset1:1
	v_cndmask_b32_e32 v10, 0, v12, vcc
	v_add_u32_e32 v147, 0x1ce8, v133
	v_cndmask_b32_e32 v11, 0, v13, vcc
	ds_write2_b32 v133, v38, v39 offset0:2 offset1:3
	ds_write2_b32 v135, v34, v35 offset1:1
	ds_write2_b32 v137, v30, v31 offset1:1
	ds_write2_b32 v139, v26, v27 offset1:1
	ds_write2_b32 v141, v22, v23 offset1:1
	ds_write2_b32 v143, v18, v19 offset1:1
	ds_write2_b32 v145, v14, v15 offset1:1
	ds_write2_b32 v147, v10, v11 offset1:1
	s_waitcnt lgkmcnt(0)
	ds_read2_b32 v[12:13], v132 offset1:8
	ds_read2_b32 v[16:17], v132 offset0:33 offset1:41
	ds_read2_b32 v[18:19], v132 offset0:66 offset1:74
	ds_read2_b32 v[20:21], v132 offset0:99 offset1:107
	ds_read2_b32 v[22:23], v132 offset0:132 offset1:140
	ds_read2_b32 v[24:25], v132 offset0:165 offset1:173
	ds_read2_b32 v[26:27], v132 offset0:198 offset1:206
	ds_read2_b32 v[28:29], v132 offset0:231 offset1:239
	v_cndmask_b32_e64 v9, v9, 1.0, s[18:19]
	v_cndmask_b32_e64 v8, v8, 1.0, s[18:19]
	v_cndmask_b32_e64 v7, v7, 1.0, s[18:19]
	v_cndmask_b32_e64 v6, v6, 1.0, s[18:19]
	v_cndmask_b32_e64 v11, v5, 1.0, s[18:19]
	v_cndmask_b32_e64 v10, v4, 1.0, s[18:19]
	v_cndmask_b32_e64 v15, v3, 1.0, s[18:19]
	v_cndmask_b32_e64 v14, v2, 1.0, s[18:19]
	s_waitcnt lgkmcnt(7)
	v_mov_b32_e32 v2, v12
	s_waitcnt lgkmcnt(6)
	v_mov_b32_e32 v3, v16
	s_waitcnt lgkmcnt(5)
	v_mov_b32_e32 v4, v18
	s_waitcnt lgkmcnt(4)
	v_mov_b32_e32 v5, v20
	v_pk_mul_f32 v[2:3], v[6:7], v[2:3]
	v_pk_mul_f32 v[4:5], v[8:9], v[4:5]
	v_cvt_pk_bf16_f32 v2, v2, v3
	v_cvt_pk_bf16_f32 v3, v4, v5
	s_waitcnt lgkmcnt(3)
	v_mov_b32_e32 v4, v22
	s_waitcnt lgkmcnt(2)
	v_mov_b32_e32 v5, v24
	s_waitcnt lgkmcnt(1)
; #define LAS __attribute__((address_space(3)))
; __device__ __forceinline__ unsigned cvtpk(float lo, float hi) { f32x2_t v = {lo, hi}; bf16x2_t b = __builtin_convertvector(v, bf16x2_t); return __builtin_bit_cast(unsigned, b); }
; #define LDS_WAIT() asm volatile("s_waitcnt lgkmcnt(0)" ::: "memory")
; #define CJ_SET(W_, K_, N_, kind_, gain_, WT_, NG_) do { j.W = (W_); j.K = (K_); j.Norig = (N_); j.kind = (kind_); j.gain = (gain_); j.WT = (bf16_t*)(WT_); j.kb = r / (NG_); j.g = r % (NG_); } while (0)
; template <int LIST> __device__ __forceinline__ ConvJob conv_job(int r, const Params& P) {
;     unsigned char* outb = (unsigned char*)P.out; ConvJob j;
;     ...
;     if (LIST == 0) CJ_SET(P.in[6], D, NUP, 1, P.in[5], outb + OW_UP1, G_UP);
;     else if (LIST == 2) CJ_SET(P.in[20], D, NUP, 1, P.in[19], outb + OW_UP2, G_UP);
;     else if (LIST == 3) CJ_SET(P.in[21], FF, D, 0, nullptr, P.ws + WS_WDN2, G_DN);
;     else if (r < I_DN) CJ_SET(P.in[7], FF, D, 0, nullptr, outb + OW_DN1, G_DN);
;     else if ((r -= I_DN) < I_IN) CJ_SET(P.in[9], D, 6672, 2, P.in[8], outb + OW_IN, G_IN);
;     else if ((r -= I_IN) < I_BR) CJ_SET(P.in[17], 2048, D, 0, nullptr, outb + OW_BR, G_BR);
;     else { r -= I_BR; CJ_SET(P.in[18], D, D, 0, nullptr, outb + OW_OUT, G_BR); }
; __device__ __forceinline__ void conv_emit(const ConvJob& j, int lane, const ConvSet& s, LAS float* scr) {
;     ...
;     for (int q = 0; q < 4; ++q) { const int nn = (lane >> 3) + 8 * q; const LAS float* sr = scr + (8 * c) * 33 + nn;
;         u32x4 o; o.x = cvtpk(sr[0 * 33] * g0[0], sr[1 * 33] * g0[1]); o.y = cvtpk(sr[2 * 33] * g0[2], sr[3 * 33] * g0[3]); o.z = cvtpk(sr[4 * 33] * g1[0], sr[5 * 33] * g1[1]); o.w = cvtpk(sr[6 * 33] * g1[2], sr[7 * 33] * g1[3]);
;         *(u32x4*)(j.WT + (size_t)(j.g * 32 + nn) * j.K + k0 + 8 * c) = o; }
;     LDS_WAIT(); asm volatile("" ::: "memory");
	v_mov_b32_e32 v30, v26
	s_waitcnt lgkmcnt(0)
	v_mov_b32_e32 v31, v28
	s_lshl_b32 s28, s72, 5
	v_pk_mul_f32 v[4:5], v[14:15], v[4:5]
	v_pk_mul_f32 v[30:31], v[10:11], v[30:31]
	v_or_b32_e32 v12, s28, v127
	s_ashr_i32 s18, s28, 31
	s_lshl_b32 s20, s73, 6
	v_cvt_pk_bf16_f32 v4, v4, v5
	v_cvt_pk_bf16_f32 v5, v30, v31
	s_mul_i32 s29, s6, s18
	v_mul_lo_u32 v16, s7, v12
	v_mad_u64_u32 v[30:31], s[18:19], s6, v12, 0
	s_ashr_i32 s21, s20, 31
	v_add3_u32 v31, v31, s29, v16
	v_lshl_add_u64 v[30:31], v[30:31], 1, s[8:9]
	s_lshl_b64 s[18:19], s[20:21], 1
	v_lshl_add_u64 v[30:31], v[30:31], 0, s[18:19]
	v_lshlrev_b32_e32 v124, 1, v128
	v_mov_b32_e32 v125, v123
	v_lshl_add_u64 v[30:31], v[30:31], 0, v[124:125]
	v_mov_b32_e32 v16, v13
	v_mov_b32_e32 v20, v19
	global_store_dwordx4 v[30:31], v[2:5], off sc1
	v_mov_b32_e32 v24, v23
	v_mov_b32_e32 v28, v27
	v_pk_mul_f32 v[2:3], v[6:7], v[16:17]
	v_pk_mul_f32 v[4:5], v[8:9], v[20:21]
	v_cvt_pk_bf16_f32 v2, v2, v3
	v_cvt_pk_bf16_f32 v3, v4, v5
	v_pk_mul_f32 v[4:5], v[14:15], v[24:25]
	v_pk_mul_f32 v[12:13], v[10:11], v[28:29]
	v_cvt_pk_bf16_f32 v4, v4, v5
	v_cvt_pk_bf16_f32 v5, v12, v13
	v_or_b32_e32 v12, s28, v129
	v_mul_lo_u32 v16, s7, v12
	v_mad_u64_u32 v[12:13], s[20:21], s6, v12, 0
	v_add3_u32 v13, v13, s29, v16
	v_lshl_add_u64 v[12:13], v[12:13], 1, s[8:9]
	v_lshl_add_u64 v[12:13], v[12:13], 0, s[18:19]
	v_lshl_add_u64 v[12:13], v[12:13], 0, v[124:125]
	ds_read2_b32 v[16:17], v132 offset0:16 offset1:24
	ds_read2_b32 v[18:19], v132 offset0:49 offset1:57
	global_store_dwordx4 v[12:13], v[2:5], off sc1
	ds_read2_b32 v[12:13], v132 offset0:82 offset1:90
	ds_read2_b32 v[20:21], v132 offset0:115 offset1:123
	ds_read2_b32 v[22:23], v132 offset0:148 offset1:156
	ds_read2_b32 v[24:25], v132 offset0:181 offset1:189
	ds_read2_b32 v[26:27], v132 offset0:214 offset1:222
	ds_read2_b32 v[28:29], v132 offset0:247 offset1:255
	s_waitcnt lgkmcnt(7)
	v_mov_b32_e32 v2, v16
	s_waitcnt lgkmcnt(6)
	v_mov_b32_e32 v3, v18
	s_waitcnt lgkmcnt(5)
	v_mov_b32_e32 v4, v12
	s_waitcnt lgkmcnt(4)
	v_mov_b32_e32 v5, v20
	v_pk_mul_f32 v[2:3], v[6:7], v[2:3]
	v_pk_mul_f32 v[4:5], v[8:9], v[4:5]
	v_cvt_pk_bf16_f32 v2, v2, v3
	v_cvt_pk_bf16_f32 v3, v4, v5
	s_waitcnt lgkmcnt(3)
	v_mov_b32_e32 v4, v22
	s_waitcnt lgkmcnt(2)
	v_mov_b32_e32 v5, v24
	s_waitcnt lgkmcnt(1)
	v_mov_b32_e32 v30, v26
	s_waitcnt lgkmcnt(0)
	v_mov_b32_e32 v31, v28
	v_pk_mul_f32 v[4:5], v[14:15], v[4:5]
	v_pk_mul_f32 v[30:31], v[10:11], v[30:31]
	v_or_b32_e32 v12, s28, v130
	v_cvt_pk_bf16_f32 v4, v4, v5
	v_cvt_pk_bf16_f32 v5, v30, v31
	v_mul_lo_u32 v16, s7, v12
	v_mad_u64_u32 v[30:31], s[20:21], s6, v12, 0
	v_add3_u32 v31, v31, s29, v16
	v_lshl_add_u64 v[30:31], v[30:31], 1, s[8:9]
	v_lshl_add_u64 v[30:31], v[30:31], 0, s[18:19]
	v_lshl_add_u64 v[30:31], v[30:31], 0, v[124:125]
	v_mov_b32_e32 v18, v17
	v_mov_b32_e32 v20, v13
	global_store_dwordx4 v[30:31], v[2:5], off sc1
	v_mov_b32_e32 v24, v23
	v_mov_b32_e32 v28, v27
	v_pk_mul_f32 v[2:3], v[6:7], v[18:19]
	v_pk_mul_f32 v[4:5], v[8:9], v[20:21]
	v_cvt_pk_bf16_f32 v2, v2, v3
	v_cvt_pk_bf16_f32 v3, v4, v5
	v_pk_mul_f32 v[4:5], v[14:15], v[24:25]
	v_pk_mul_f32 v[6:7], v[10:11], v[28:29]
	v_cvt_pk_bf16_f32 v4, v4, v5
	v_cvt_pk_bf16_f32 v5, v6, v7
	v_or_b32_e32 v6, s28, v131
	v_mul_lo_u32 v8, s7, v6
	v_mad_u64_u32 v[6:7], s[6:7], s6, v6, 0
	v_add3_u32 v7, v7, s29, v8
	v_lshl_add_u64 v[6:7], v[6:7], 1, s[8:9]
	v_lshl_add_u64 v[6:7], v[6:7], 0, s[18:19]
	v_lshl_add_u64 v[6:7], v[6:7], 0, v[124:125]
	global_store_dwordx4 v[6:7], v[2:5], off sc1
	s_waitcnt lgkmcnt(0)
	s_add_i32 s72, s24, s25
	s_min_i32 s75, s72, 0x18ff
	s_cmpk_gt_i32 s72, 0x57f
	s_cbranch_scc0 .LBB0_479
	s_cmpk_gt_u32 s72, 0x12ff
	s_mov_b64 s[20:21], -1
	s_cbranch_scc0 .LBB0_480
	s_cmpk_gt_u32 s72, 0x16ff
	s_cbranch_scc0 .LBB0_481
	s_add_i32 s6, s75, 0xffffe900
	s_lshr_b32 s73, s6, 5
	s_mov_b64 s[6:7], s[40:41]
	s_cbranch_execz .LBB0_482
	s_branch .LBB0_483

; #define LAS __attribute__((address_space(3)))
; __device__ __forceinline__ unsigned cvtpk(float lo, float hi) { f32x2_t v = {lo, hi}; bf16x2_t b = __builtin_convertvector(v, bf16x2_t); return __builtin_bit_cast(unsigned, b); }
; #define LDS_WAIT() asm volatile("s_waitcnt lgkmcnt(0)" ::: "memory")
; __device__ __forceinline__ void conv_emit(const ConvJob& j, int lane, const ConvSet& s, LAS float* scr) {
;     const int k0 = 64 * j.kb; int cnt; (void)vgroup_src(j.kind, j.g, cnt);
;     const int ks = lane >> 3, n4 = (lane & 7) * 4, c = lane & 7; const bool okc = n4 < cnt;
;     const f32x4 one = (f32x4){1.f, 1.f, 1.f, 1.f}; const f32x4 g0 = j.gain ? s.g0 : one, g1 = j.gain ? s.g1 : one;
; #pragma unroll
;     for (int i = 0; i < 8; ++i) { LAS float* sp = scr + (8 * i + ks) * 33 + n4;
; #pragma unroll
;         for (int e = 0; e < 4; ++e) sp[e] = okc ? s.v[i][e] : 0.f; }
;     LDS_WAIT(); asm volatile("" ::: "memory");
; #pragma unroll
;     for (int q = 0; q < 4; ++q) { const int nn = (lane >> 3) + 8 * q; const LAS float* sr = scr + (8 * c) * 33 + nn;
;         u32x4 o; o.x = cvtpk(sr[0 * 33] * g0[0], sr[1 * 33] * g0[1]); o.y = cvtpk(sr[2 * 33] * g0[2], sr[3 * 33] * g0[3]); o.z = cvtpk(sr[4 * 33] * g1[0], sr[5 * 33] * g1[1]); o.w = cvtpk(sr[6 * 33] * g1[2], sr[7 * 33] * g1[3]);
;         *(u32x4*)(j.WT + (size_t)(j.g * 32 + nn) * j.K + k0 + 8 * c) = o; }
;     LDS_WAIT(); asm volatile("" ::: "memory");
.LBB0_503:
	s_cmpk_lt_i32 s73, 0xd0
	s_cselect_b64 s[28:29], -1, 0
	s_and_b32 s75, s73, 7
	s_cmp_eq_u32 s75, 0
	s_cselect_b32 s75, 16, 0
	s_or_b64 s[20:21], s[20:21], s[28:29]
	s_and_b64 s[20:21], s[20:21], exec
	s_cselect_b32 s20, 32, s75
	v_cmp_gt_u32_e32 vcc, s20, v126
	s_waitcnt vmcnt(32)
	v_cndmask_b32_e64 v49, v49, 1.0, s[18:19]
	v_cndmask_b32_e64 v48, v48, 1.0, s[18:19]
	s_waitcnt vmcnt(30)
	v_cndmask_b32_e32 v70, 0, v70, vcc
	v_cndmask_b32_e32 v71, 0, v71, vcc
	s_waitcnt vmcnt(28)
	v_cndmask_b32_e32 v62, 0, v62, vcc
	v_cndmask_b32_e32 v63, 0, v63, vcc
	s_waitcnt vmcnt(26)
	v_cndmask_b32_e32 v54, 0, v54, vcc
	v_cndmask_b32_e32 v55, 0, v55, vcc
	ds_write2_b32 v134, v70, v71 offset1:1
	v_cndmask_b32_e32 v70, 0, v72, vcc
	v_cndmask_b32_e32 v71, 0, v73, vcc
	ds_write2_b32 v138, v62, v63 offset1:1
	v_cndmask_b32_e32 v62, 0, v64, vcc
	v_cndmask_b32_e32 v63, 0, v65, vcc
	ds_write2_b32 v142, v54, v55 offset1:1
	v_cndmask_b32_e32 v54, 0, v56, vcc
	v_cndmask_b32_e32 v55, 0, v57, vcc
	v_cndmask_b32_e32 v78, 0, v78, vcc
	v_cndmask_b32_e32 v79, 0, v79, vcc
	ds_write2_b32 v135, v70, v71 offset1:1
	v_cndmask_b32_e32 v70, 0, v74, vcc
	v_cndmask_b32_e32 v71, 0, v75, vcc
	ds_write2_b32 v139, v62, v63 offset1:1
	v_cndmask_b32_e32 v62, 0, v66, vcc
	v_cndmask_b32_e32 v63, 0, v67, vcc
	ds_write2_b32 v143, v54, v55 offset1:1
	s_waitcnt vmcnt(25)
	v_cndmask_b32_e32 v54, 0, v58, vcc
	v_cndmask_b32_e32 v55, 0, v59, vcc
	s_waitcnt vmcnt(24)
	v_cndmask_b32_e32 v50, 0, v50, vcc
	v_cndmask_b32_e32 v51, 0, v51, vcc
	ds_write2_b32 v133, v78, v79 offset1:1
	v_cndmask_b32_e32 v78, 0, v80, vcc
	v_cndmask_b32_e32 v79, 0, v81, vcc
	ds_write2_b32 v136, v70, v71 offset1:1
	v_cndmask_b32_e32 v70, 0, v76, vcc
	v_cndmask_b32_e32 v71, 0, v77, vcc
	ds_write2_b32 v140, v62, v63 offset1:1
	v_cndmask_b32_e32 v62, 0, v68, vcc
	v_cndmask_b32_e32 v63, 0, v69, vcc
	ds_write2_b32 v144, v54, v55 offset1:1
	v_cndmask_b32_e32 v54, 0, v60, vcc
	v_cndmask_b32_e32 v55, 0, v61, vcc
	ds_write2_b32 v146, v50, v51 offset1:1
	v_cndmask_b32_e32 v50, 0, v52, vcc
	v_cndmask_b32_e32 v51, 0, v53, vcc
	ds_write2_b32 v133, v78, v79 offset0:2 offset1:3
	ds_write2_b32 v137, v70, v71 offset1:1
	ds_write2_b32 v141, v62, v63 offset1:1
	ds_write2_b32 v145, v54, v55 offset1:1
	ds_write2_b32 v147, v50, v51 offset1:1
	s_waitcnt lgkmcnt(0)
	ds_read2_b32 v[52:53], v132 offset1:8
	ds_read2_b32 v[56:57], v132 offset0:33 offset1:41
	ds_read2_b32 v[58:59], v132 offset0:66 offset1:74
	ds_read2_b32 v[60:61], v132 offset0:99 offset1:107
	ds_read2_b32 v[62:63], v132 offset0:132 offset1:140
	ds_read2_b32 v[64:65], v132 offset0:165 offset1:173
	ds_read2_b32 v[66:67], v132 offset0:198 offset1:206
	ds_read2_b32 v[68:69], v132 offset0:231 offset1:239
	v_cndmask_b32_e64 v47, v47, 1.0, s[18:19]
	v_cndmask_b32_e64 v46, v46, 1.0, s[18:19]
	v_cndmask_b32_e64 v51, v45, 1.0, s[18:19]
	v_cndmask_b32_e64 v50, v44, 1.0, s[18:19]
	v_cndmask_b32_e64 v55, v43, 1.0, s[18:19]
	v_cndmask_b32_e64 v54, v42, 1.0, s[18:19]
	s_waitcnt lgkmcnt(7)
	v_mov_b32_e32 v42, v52
	s_waitcnt lgkmcnt(6)
	v_mov_b32_e32 v43, v56
	s_waitcnt lgkmcnt(5)
	v_mov_b32_e32 v44, v58
	s_waitcnt lgkmcnt(4)
	v_mov_b32_e32 v45, v60
	v_pk_mul_f32 v[42:43], v[46:47], v[42:43]
	v_pk_mul_f32 v[44:45], v[48:49], v[44:45]
	v_cvt_pk_bf16_f32 v42, v42, v43
	v_cvt_pk_bf16_f32 v43, v44, v45
	s_waitcnt lgkmcnt(3)
	v_mov_b32_e32 v44, v62
	s_waitcnt lgkmcnt(2)
	v_mov_b32_e32 v45, v64
	s_waitcnt lgkmcnt(1)
	v_mov_b32_e32 v70, v66
	s_waitcnt lgkmcnt(0)
	v_mov_b32_e32 v71, v68
	s_lshl_b32 s28, s73, 5
	v_pk_mul_f32 v[44:45], v[54:55], v[44:45]
	v_pk_mul_f32 v[70:71], v[50:51], v[70:71]
	v_or_b32_e32 v52, s28, v127
	s_ashr_i32 s18, s28, 31
	s_lshl_b32 s20, s74, 6
	v_cvt_pk_bf16_f32 v44, v44, v45
	v_cvt_pk_bf16_f32 v45, v70, v71
	s_mul_i32 s29, s6, s18
	v_mul_lo_u32 v56, s7, v52
	v_mad_u64_u32 v[70:71], s[18:19], s6, v52, 0
	s_ashr_i32 s21, s20, 31
	v_add3_u32 v71, v71, s29, v56
	v_lshl_add_u64 v[70:71], v[70:71], 1, s[8:9]
	s_lshl_b64 s[18:19], s[20:21], 1
	v_lshl_add_u64 v[70:71], v[70:71], 0, s[18:19]
	v_mov_b32_e32 v125, v123
	v_lshl_add_u64 v[70:71], v[70:71], 0, v[124:125]
	v_mov_b32_e32 v56, v53
	v_mov_b32_e32 v60, v59
	global_store_dwordx4 v[70:71], v[42:45], off sc1
	v_mov_b32_e32 v64, v63
	v_mov_b32_e32 v68, v67
	v_pk_mul_f32 v[42:43], v[46:47], v[56:57]
	v_pk_mul_f32 v[44:45], v[48:49], v[60:61]
	v_cvt_pk_bf16_f32 v42, v42, v43
	v_cvt_pk_bf16_f32 v43, v44, v45
	v_pk_mul_f32 v[44:45], v[54:55], v[64:65]
	v_pk_mul_f32 v[52:53], v[50:51], v[68:69]
	v_cvt_pk_bf16_f32 v44, v44, v45
	v_cvt_pk_bf16_f32 v45, v52, v53
	v_or_b32_e32 v52, s28, v129
	v_mul_lo_u32 v56, s7, v52
	v_mad_u64_u32 v[52:53], s[20:21], s6, v52, 0
	v_add3_u32 v53, v53, s29, v56
	v_lshl_add_u64 v[52:53], v[52:53], 1, s[8:9]
	v_lshl_add_u64 v[52:53], v[52:53], 0, s[18:19]
	v_lshl_add_u64 v[52:53], v[52:53], 0, v[124:125]
	ds_read2_b32 v[56:57], v132 offset0:16 offset1:24
	ds_read2_b32 v[58:59], v132 offset0:49 offset1:57
	global_store_dwordx4 v[52:53], v[42:45], off sc1
	ds_read2_b32 v[52:53], v132 offset0:82 offset1:90
	ds_read2_b32 v[60:61], v132 offset0:115 offset1:123
	ds_read2_b32 v[62:63], v132 offset0:148 offset1:156
	ds_read2_b32 v[64:65], v132 offset0:181 offset1:189
	ds_read2_b32 v[66:67], v132 offset0:214 offset1:222
	ds_read2_b32 v[68:69], v132 offset0:247 offset1:255
	s_waitcnt lgkmcnt(7)
	v_mov_b32_e32 v42, v56
	s_waitcnt lgkmcnt(6)
	v_mov_b32_e32 v43, v58
	s_waitcnt lgkmcnt(5)
	v_mov_b32_e32 v44, v52
	s_waitcnt lgkmcnt(4)
	v_mov_b32_e32 v45, v60
	v_pk_mul_f32 v[42:43], v[46:47], v[42:43]
	v_pk_mul_f32 v[44:45], v[48:49], v[44:45]
	v_cvt_pk_bf16_f32 v42, v42, v43
	v_cvt_pk_bf16_f32 v43, v44, v45
	s_waitcnt lgkmcnt(3)
	v_mov_b32_e32 v44, v62
	s_waitcnt lgkmcnt(2)
	v_mov_b32_e32 v45, v64
	s_waitcnt lgkmcnt(1)
	v_mov_b32_e32 v70, v66
	s_waitcnt lgkmcnt(0)
	v_mov_b32_e32 v71, v68
	v_pk_mul_f32 v[44:45], v[54:55], v[44:45]
	v_pk_mul_f32 v[70:71], v[50:51], v[70:71]
	v_or_b32_e32 v52, s28, v130
	v_cvt_pk_bf16_f32 v44, v44, v45
	v_cvt_pk_bf16_f32 v45, v70, v71
	v_mul_lo_u32 v56, s7, v52
	v_mad_u64_u32 v[70:71], s[20:21], s6, v52, 0
	v_add3_u32 v71, v71, s29, v56
	v_lshl_add_u64 v[70:71], v[70:71], 1, s[8:9]
	v_lshl_add_u64 v[70:71], v[70:71], 0, s[18:19]
	v_lshl_add_u64 v[70:71], v[70:71], 0, v[124:125]
	v_mov_b32_e32 v58, v57
	v_mov_b32_e32 v60, v53
	global_store_dwordx4 v[70:71], v[42:45], off sc1
	v_mov_b32_e32 v64, v63
	v_mov_b32_e32 v68, v67
	v_pk_mul_f32 v[42:43], v[46:47], v[58:59]
	v_pk_mul_f32 v[44:45], v[48:49], v[60:61]
	v_cvt_pk_bf16_f32 v42, v42, v43
	v_cvt_pk_bf16_f32 v43, v44, v45
	v_pk_mul_f32 v[44:45], v[54:55], v[64:65]
	v_pk_mul_f32 v[46:47], v[50:51], v[68:69]
	v_cvt_pk_bf16_f32 v44, v44, v45
	v_cvt_pk_bf16_f32 v45, v46, v47
	v_or_b32_e32 v46, s28, v131
	v_mul_lo_u32 v48, s7, v46
	v_mad_u64_u32 v[46:47], s[6:7], s6, v46, 0
	v_add3_u32 v47, v47, s29, v48
	v_lshl_add_u64 v[46:47], v[46:47], 1, s[8:9]
	v_lshl_add_u64 v[46:47], v[46:47], 0, s[18:19]
	v_lshl_add_u64 v[46:47], v[46:47], 0, v[124:125]
	global_store_dwordx4 v[46:47], v[42:45], off sc1
	s_waitcnt lgkmcnt(0)

; template <int LIST> __device__ __forceinline__ ConvJob conv_job(int r, const Params& P) {
;     unsigned char* outb = (unsigned char*)P.out; ConvJob j;
;     ...
;     if (LIST == 0) CJ_SET(P.in[6], D, NUP, 1, P.in[5], outb + OW_UP1, G_UP);
;     else if (LIST == 2) CJ_SET(P.in[20], D, NUP, 1, P.in[19], outb + OW_UP2, G_UP);
;     else if (LIST == 3) CJ_SET(P.in[21], FF, D, 0, nullptr, P.ws + WS_WDN2, G_DN);
;     else if (r < I_DN) CJ_SET(P.in[7], FF, D, 0, nullptr, outb + OW_DN1, G_DN);
;     else if ((r -= I_DN) < I_IN) CJ_SET(P.in[9], D, 6672, 2, P.in[8], outb + OW_IN, G_IN);
;     else if ((r -= I_IN) < I_BR) CJ_SET(P.in[17], 2048, D, 0, nullptr, outb + OW_BR, G_BR);
;     else { r -= I_BR; CJ_SET(P.in[18], D, D, 0, nullptr, outb + OW_OUT, G_BR); }
;     ...
;     return j;
; }
; __device__ __forceinline__ void conv_fetch(const ConvJob& j, int lane, ConvSet& s) {
;     const int k0 = 64 * j.kb; int cnt; const int src = vgroup_src(j.kind, j.g, cnt);
;     const int ks = lane >> 3, n4 = (lane & 7) * 4, c = lane & 7; const bool okc = n4 < cnt;
;     const float* gp = j.gain ? j.gain + k0 + 8 * c : j.W;
;     s.g0 = *(const f32x4*)gp; s.g1 = *(const f32x4*)(gp + 4);
;     const float* wp = j.W + (size_t)(k0 + ks) * j.Norig + src + (okc ? n4 : 0);
; #pragma unroll
;     for (int i = 0; i < 8; ++i) s.v[i] = *(const f32x4*)(wp + (size_t)(8 * i) * j.Norig);
; }
; __device__ __forceinline__ void conv_emit(const ConvJob& j, int lane, const ConvSet& s, LAS float* scr) {
;     const int k0 = 64 * j.kb; int cnt; (void)vgroup_src(j.kind, j.g, cnt);
;     const int ks = lane >> 3, n4 = (lane & 7) * 4, c = lane & 7; const bool okc = n4 < cnt;
;     const f32x4 one = (f32x4){1.f, 1.f, 1.f, 1.f}; const f32x4 g0 = j.gain ? s.g0 : one, g1 = j.gain ? s.g1 : one;
; #pragma unroll
;     for (int i = 0; i < 8; ++i) { LAS float* sp = scr + (8 * i + ks) * 33 + n4;
; #pragma unroll
;         for (int e = 0; e < 4; ++e) sp[e] = okc ? s.v[i][e] : 0.f; }
;     LDS_WAIT(); asm volatile("" ::: "memory");
; #pragma unroll
;     for (int q = 0; q < 4; ++q) { const int nn = (lane >> 3) + 8 * q; const LAS float* sr = scr + (8 * c) * 33 + nn;
;         u32x4 o; o.x = cvtpk(sr[0 * 33] * g0[0], sr[1 * 33] * g0[1]); o.y = cvtpk(sr[2 * 33] * g0[2], sr[3 * 33] * g0[3]); o.z = cvtpk(sr[4 * 33] * g1[0], sr[5 * 33] * g1[1]); o.w = cvtpk(sr[6 * 33] * g1[2], sr[7 * 33] * g1[3]);
.LBB0_795:
	s_add_i32 s34, s8, s28
	s_add_i32 s29, s27, s28
	s_cmpk_lt_i32 s29, 0xb00
	s_cselect_b64 s[4:5], -1, 0
	s_and_b64 s[6:7], s[4:5], exec
	s_cselect_b32 s6, s29, 0xaff
	s_mul_hi_i32 s7, s6, 0x2e8ba2e9
	s_lshr_b32 s30, s7, 31
	s_ashr_i32 s7, s7, 5
	s_add_i32 s7, s7, s30
	s_mul_i32 s30, s7, 0xb0
	s_sub_i32 s30, s6, s30
	s_lshl_b32 s6, s7, 6
	s_bfe_i32 s7, s30, 0x10002
	s_lshl_b32 s31, s30, 4
	s_and_b32 s7, s7, 0xb00
	s_and_b32 s31, s31, 0xffffff80
	s_lshl_b32 s30, s30, 5
	s_add_i32 s7, s7, s31
	s_and_b32 s30, s30, 0x60
	s_or_b32 s30, s7, s30
	s_ashr_i32 s7, s6, 31
	s_waitcnt vmcnt(31)
	v_or_b32_e32 v90, s6, v130
	v_mov_b64_e32 v[128:129], s[44:45]
	v_lshl_add_u64 v[82:83], s[6:7], 2, v[124:125]
	v_mad_i64_i32 v[90:91], s[6:7], v90, s9, v[128:129]
	s_ashr_i32 s31, s30, 31
	v_lshl_add_u64 v[90:91], s[30:31], 2, v[90:91]
	s_waitcnt vmcnt(25)
	v_lshl_add_u64 v[114:115], v[90:91], 0, v[122:123]
	v_add_co_u32_e32 v94, vcc, s10, v114
	v_mov_b32_e32 v150, s45
	s_nop 0
	v_addc_co_u32_e32 v95, vcc, 0, v115, vcc
	v_add_co_u32_e32 v98, vcc, s11, v114
	v_mov_b32_e32 v151, s44
	s_nop 0
	v_addc_co_u32_e32 v99, vcc, 0, v115, vcc
	v_add_co_u32_e32 v102, vcc, s18, v114
	v_cndmask_b32_e64 v87, v83, v150, s[0:1]
	s_nop 0
	v_addc_co_u32_e32 v103, vcc, 0, v115, vcc
	v_add_co_u32_e32 v106, vcc, s19, v114
	v_cndmask_b32_e64 v86, v82, v151, s[0:1]
	s_nop 0
	v_addc_co_u32_e32 v107, vcc, 0, v115, vcc
	v_add_co_u32_e32 v110, vcc, s20, v114
	v_add_u32_e32 v136, 0x420, v135
	s_nop 0
	v_addc_co_u32_e32 v111, vcc, 0, v115, vcc
	v_add_co_u32_e32 v116, vcc, s21, v114
	v_add_u32_e32 v137, 0x428, v135
	s_nop 0
	v_addc_co_u32_e32 v117, vcc, 0, v115, vcc
	s_waitcnt vmcnt(24)
	v_add_co_u32_e32 v118, vcc, s22, v114
	v_add_u32_e32 v138, 0x840, v135
	s_nop 0
	v_addc_co_u32_e32 v119, vcc, 0, v115, vcc
	v_add_u32_e32 v139, 0x848, v135
	v_add_u32_e32 v140, 0xc60, v135
	v_add_u32_e32 v141, 0xc68, v135
	v_add_u32_e32 v142, 0x1080, v135
	v_add_u32_e32 v143, 0x1088, v135
	v_add_u32_e32 v144, 0x14a0, v135
	v_add_u32_e32 v145, 0x14a8, v135
	v_add_u32_e32 v146, 0x18c0, v135
	v_add_u32_e32 v147, 0x18c8, v135
	v_add_u32_e32 v148, 0x1ce0, v135
	v_add_u32_e32 v149, 0x1ce8, v135
	global_load_dwordx4 v[82:85], v[86:87], off offset:16
	s_nop 0
	global_load_dwordx4 v[86:89], v[86:87], off
	s_nop 0
	global_load_dwordx4 v[90:93], v[114:115], off
	s_nop 0
	global_load_dwordx4 v[94:97], v[94:95], off
	s_nop 0
	global_load_dwordx4 v[98:101], v[98:99], off
	s_nop 0
	global_load_dwordx4 v[102:105], v[102:103], off
	s_nop 0
	global_load_dwordx4 v[106:109], v[106:107], off
	s_nop 0
	global_load_dwordx4 v[110:113], v[110:111], off
	s_nop 0
	global_load_dwordx4 v[114:117], v[116:117], off
	s_nop 0
	global_load_dwordx4 v[118:121], v[118:119], off
	s_waitcnt vmcnt(27)
	ds_write2_b32 v135, v10, v11 offset1:1
	ds_write2_b32 v135, v12, v13 offset0:2 offset1:3
	s_waitcnt vmcnt(26)
	ds_write2_b32 v136, v14, v15 offset1:1
	ds_write2_b32 v137, v16, v17 offset1:1
	s_waitcnt vmcnt(25)
	ds_write2_b32 v138, v22, v23 offset1:1
	ds_write2_b32 v139, v24, v25 offset1:1
	s_waitcnt vmcnt(24)
	ds_write2_b32 v140, v26, v27 offset1:1
	ds_write2_b32 v141, v28, v29 offset1:1
	s_waitcnt vmcnt(23)
	ds_write2_b32 v142, v34, v35 offset1:1
	ds_write2_b32 v143, v36, v37 offset1:1
	s_waitcnt vmcnt(22)
	ds_write2_b32 v144, v38, v39 offset1:1
	ds_write2_b32 v145, v40, v41 offset1:1
	s_waitcnt vmcnt(21)
	ds_write2_b32 v146, v42, v43 offset1:1
	ds_write2_b32 v147, v44, v45 offset1:1
	s_waitcnt vmcnt(20)
	ds_write2_b32 v148, v46, v47 offset1:1
	ds_write2_b32 v149, v48, v49 offset1:1
	s_waitcnt lgkmcnt(0)
	ds_read2_b32 v[12:13], v134 offset1:8
	ds_read2_b32 v[16:17], v134 offset0:33 offset1:41
	ds_read2_b32 v[22:23], v134 offset0:66 offset1:74
	ds_read2_b32 v[24:25], v134 offset0:99 offset1:107
	ds_read2_b32 v[26:27], v134 offset0:132 offset1:140
	ds_read2_b32 v[28:29], v134 offset0:165 offset1:173
	ds_read2_b32 v[34:35], v134 offset0:198 offset1:206
	ds_read2_b32 v[36:37], v134 offset0:231 offset1:239
	s_mul_hi_i32 s6, s34, 0x2e8ba2e9
	s_lshr_b32 s7, s6, 31
	s_ashr_i32 s6, s6, 5
	s_add_i32 s6, s6, s7
	v_cndmask_b32_e64 v9, v9, 1.0, s[0:1]
	v_cndmask_b32_e64 v8, v8, 1.0, s[0:1]
	v_cndmask_b32_e64 v7, v7, 1.0, s[0:1]
	v_cndmask_b32_e64 v6, v6, 1.0, s[0:1]
	v_cndmask_b32_e64 v11, v5, 1.0, s[0:1]
	v_cndmask_b32_e64 v10, v4, 1.0, s[0:1]
	v_cndmask_b32_e64 v15, v3, 1.0, s[0:1]
	v_cndmask_b32_e64 v14, v2, 1.0, s[0:1]
	s_waitcnt lgkmcnt(7)
	v_mov_b32_e32 v2, v12
	s_waitcnt lgkmcnt(6)
	v_mov_b32_e32 v3, v16
	s_waitcnt lgkmcnt(5)
	v_mov_b32_e32 v4, v22
	s_waitcnt lgkmcnt(4)
	v_mov_b32_e32 v5, v24
	s_mul_i32 s7, s6, 0xb0
	v_pk_mul_f32 v[2:3], v[6:7], v[2:3]
	v_pk_mul_f32 v[4:5], v[8:9], v[4:5]
	s_sub_i32 s30, s34, s7
	v_cvt_pk_bf16_f32 v2, v2, v3
	v_cvt_pk_bf16_f32 v3, v4, v5
	s_waitcnt lgkmcnt(3)
	v_mov_b32_e32 v4, v26
	s_waitcnt lgkmcnt(2)
	v_mov_b32_e32 v5, v28
	s_waitcnt lgkmcnt(1)
	v_mov_b32_e32 v38, v34
	s_waitcnt lgkmcnt(0)
; #define LAS __attribute__((address_space(3)))
; __device__ __forceinline__ unsigned cvtpk(float lo, float hi) { f32x2_t v = {lo, hi}; bf16x2_t b = __builtin_convertvector(v, bf16x2_t); return __builtin_bit_cast(unsigned, b); }
; #define LDS_WAIT() asm volatile("s_waitcnt lgkmcnt(0)" ::: "memory")
; __device__ __forceinline__ void conv_fetch(const ConvJob& j, int lane, ConvSet& s) {
;     const int k0 = 64 * j.kb; int cnt; const int src = vgroup_src(j.kind, j.g, cnt);
;     const int ks = lane >> 3, n4 = (lane & 7) * 4, c = lane & 7; const bool okc = n4 < cnt;
;     const float* gp = j.gain ? j.gain + k0 + 8 * c : j.W;
;     s.g0 = *(const f32x4*)gp; s.g1 = *(const f32x4*)(gp + 4);
;     const float* wp = j.W + (size_t)(k0 + ks) * j.Norig + src + (okc ? n4 : 0);
; #pragma unroll
;     for (int i = 0; i < 8; ++i) s.v[i] = *(const f32x4*)(wp + (size_t)(8 * i) * j.Norig);
; }
; __device__ __forceinline__ void conv_emit(const ConvJob& j, int lane, const ConvSet& s, LAS float* scr) {
;     const int k0 = 64 * j.kb; int cnt; (void)vgroup_src(j.kind, j.g, cnt);
;     const int ks = lane >> 3, n4 = (lane & 7) * 4, c = lane & 7; const bool okc = n4 < cnt;
;     const f32x4 one = (f32x4){1.f, 1.f, 1.f, 1.f}; const f32x4 g0 = j.gain ? s.g0 : one, g1 = j.gain ? s.g1 : one;
; #pragma unroll
;     for (int i = 0; i < 8; ++i) { LAS float* sp = scr + (8 * i + ks) * 33 + n4;
; #pragma unroll
;         for (int e = 0; e < 4; ++e) sp[e] = okc ? s.v[i][e] : 0.f; }
;     LDS_WAIT(); asm volatile("" ::: "memory");
; #pragma unroll
;     for (int q = 0; q < 4; ++q) { const int nn = (lane >> 3) + 8 * q; const LAS float* sr = scr + (8 * c) * 33 + nn;
;         u32x4 o; o.x = cvtpk(sr[0 * 33] * g0[0], sr[1 * 33] * g0[1]); o.y = cvtpk(sr[2 * 33] * g0[2], sr[3 * 33] * g0[3]); o.z = cvtpk(sr[4 * 33] * g1[0], sr[5 * 33] * g1[1]); o.w = cvtpk(sr[6 * 33] * g1[2], sr[7 * 33] * g1[3]);
;         *(u32x4*)(j.WT + (size_t)(j.g * 32 + nn) * j.K + k0 + 8 * c) = o; }
	v_mov_b32_e32 v39, v36
	v_pk_mul_f32 v[4:5], v[14:15], v[4:5]
	v_pk_mul_f32 v[38:39], v[10:11], v[38:39]
	s_lshl_b32 s30, s30, 5
	v_cvt_pk_bf16_f32 v4, v4, v5
	v_cvt_pk_bf16_f32 v5, v38, v39
	v_or_b32_e32 v38, s30, v130
	s_lshl_b32 s6, s6, 6
	v_ashrrev_i32_e32 v39, 31, v38
	v_readlane_b32 s34, v252, 9
	s_ashr_i32 s7, s6, 31
	v_lshlrev_b64 v[38:39], 11, v[38:39]
	v_readlane_b32 s35, v252, 10
	s_lshl_b64 s[6:7], s[6:7], 1
	v_mov_b32_e32 v127, v123
	v_lshl_add_u64 v[38:39], s[34:35], 0, v[38:39]
	v_lshl_add_u64 v[38:39], v[38:39], 0, s[6:7]
	v_lshl_add_u64 v[38:39], v[38:39], 0, v[126:127]
	v_mov_b32_e32 v16, v13
	v_mov_b32_e32 v24, v23
	global_store_dwordx4 v[38:39], v[2:5], off sc1
	v_mov_b32_e32 v28, v27
	v_mov_b32_e32 v36, v35
	v_pk_mul_f32 v[2:3], v[6:7], v[16:17]
	v_pk_mul_f32 v[4:5], v[8:9], v[24:25]
	v_cvt_pk_bf16_f32 v2, v2, v3
	v_cvt_pk_bf16_f32 v3, v4, v5
	v_pk_mul_f32 v[4:5], v[14:15], v[28:29]
	v_pk_mul_f32 v[12:13], v[10:11], v[36:37]
	v_cvt_pk_bf16_f32 v4, v4, v5
	v_cvt_pk_bf16_f32 v5, v12, v13
	v_or_b32_e32 v12, s30, v131
	v_ashrrev_i32_e32 v13, 31, v12
	v_lshlrev_b64 v[12:13], 11, v[12:13]
	v_lshl_add_u64 v[12:13], s[34:35], 0, v[12:13]
	v_lshl_add_u64 v[12:13], v[12:13], 0, s[6:7]
	v_lshl_add_u64 v[12:13], v[12:13], 0, v[126:127]
	ds_read2_b32 v[16:17], v134 offset0:16 offset1:24
	ds_read2_b32 v[22:23], v134 offset0:49 offset1:57
	global_store_dwordx4 v[12:13], v[2:5], off sc1
	ds_read2_b32 v[12:13], v134 offset0:82 offset1:90
	ds_read2_b32 v[24:25], v134 offset0:115 offset1:123
	ds_read2_b32 v[26:27], v134 offset0:148 offset1:156
	ds_read2_b32 v[28:29], v134 offset0:181 offset1:189
	ds_read2_b32 v[34:35], v134 offset0:214 offset1:222
	ds_read2_b32 v[36:37], v134 offset0:247 offset1:255
	s_waitcnt lgkmcnt(7)
	v_mov_b32_e32 v2, v16
	s_waitcnt lgkmcnt(6)
	v_mov_b32_e32 v3, v22
	s_waitcnt lgkmcnt(5)
	v_mov_b32_e32 v4, v12
	s_waitcnt lgkmcnt(4)
	v_mov_b32_e32 v5, v24
	v_pk_mul_f32 v[2:3], v[6:7], v[2:3]
	v_pk_mul_f32 v[4:5], v[8:9], v[4:5]
	v_cvt_pk_bf16_f32 v2, v2, v3
	v_cvt_pk_bf16_f32 v3, v4, v5
	s_waitcnt lgkmcnt(3)
	v_mov_b32_e32 v4, v26
	s_waitcnt lgkmcnt(2)
	v_mov_b32_e32 v5, v28
	s_waitcnt lgkmcnt(1)
	v_mov_b32_e32 v38, v34
	s_waitcnt lgkmcnt(0)
	v_mov_b32_e32 v39, v36
	v_pk_mul_f32 v[4:5], v[14:15], v[4:5]
	v_pk_mul_f32 v[38:39], v[10:11], v[38:39]
	v_cvt_pk_bf16_f32 v4, v4, v5
	v_cvt_pk_bf16_f32 v5, v38, v39
	v_or_b32_e32 v38, s30, v132
	v_ashrrev_i32_e32 v39, 31, v38
	v_lshlrev_b64 v[38:39], 11, v[38:39]
	v_lshl_add_u64 v[38:39], s[34:35], 0, v[38:39]
	v_lshl_add_u64 v[38:39], v[38:39], 0, s[6:7]
	v_lshl_add_u64 v[38:39], v[38:39], 0, v[126:127]
	v_mov_b32_e32 v22, v17
	v_mov_b32_e32 v24, v13
	global_store_dwordx4 v[38:39], v[2:5], off sc1
	v_mov_b32_e32 v28, v27
	v_mov_b32_e32 v36, v35
	v_pk_mul_f32 v[2:3], v[6:7], v[22:23]
	v_pk_mul_f32 v[4:5], v[8:9], v[24:25]
	v_cvt_pk_bf16_f32 v2, v2, v3
	v_cvt_pk_bf16_f32 v3, v4, v5
	v_pk_mul_f32 v[4:5], v[14:15], v[28:29]
	v_pk_mul_f32 v[6:7], v[10:11], v[36:37]
	v_cvt_pk_bf16_f32 v4, v4, v5
	v_cvt_pk_bf16_f32 v5, v6, v7
	v_or_b32_e32 v6, s30, v133
	v_ashrrev_i32_e32 v7, 31, v6
	v_lshlrev_b64 v[6:7], 11, v[6:7]
	v_lshl_add_u64 v[6:7], s[34:35], 0, v[6:7]
	v_lshl_add_u64 v[6:7], v[6:7], 0, s[6:7]
	s_add_i32 s6, s24, s28
	s_min_i32 s6, s6, 0xaff
	s_mul_hi_i32 s7, s6, 0x2e8ba2e9
	s_lshr_b32 s30, s7, 31
	s_ashr_i32 s7, s7, 5
	s_add_i32 s7, s7, s30
	s_mul_i32 s30, s7, 0xb0
	s_sub_i32 s30, s6, s30
	s_lshl_b32 s6, s7, 6
	s_bfe_i32 s7, s30, 0x10002
	s_lshl_b32 s31, s30, 4
	s_and_b32 s7, s7, 0xb00
	s_and_b32 s31, s31, 0xffffff80
	s_lshl_b32 s30, s30, 5
	s_add_i32 s7, s7, s31
	s_and_b32 s30, s30, 0x60
	v_lshl_add_u64 v[6:7], v[6:7], 0, v[126:127]
	s_or_b32 s30, s7, s30
	s_ashr_i32 s7, s6, 31
	v_or_b32_e32 v10, s6, v130
	global_store_dwordx4 v[6:7], v[2:5], off sc1
	s_ashr_i32 s31, s30, 31
	s_waitcnt lgkmcnt(0)
	s_nop 0
	v_lshl_add_u64 v[2:3], s[6:7], 2, v[124:125]
	v_mad_i64_i32 v[10:11], s[6:7], v10, s9, v[128:129]
	v_lshl_add_u64 v[10:11], s[30:31], 2, v[10:11]
	v_lshl_add_u64 v[42:43], v[10:11], 0, v[122:123]
	v_add_co_u32_e32 v14, vcc, s10, v42
	v_cndmask_b32_e64 v7, v3, v150, s[0:1]
	s_nop 0
	v_addc_co_u32_e32 v15, vcc, 0, v43, vcc
	v_add_co_u32_e32 v22, vcc, s11, v42
	v_cndmask_b32_e64 v6, v2, v151, s[0:1]
	s_nop 0
	v_addc_co_u32_e32 v23, vcc, 0, v43, vcc
	v_add_co_u32_e32 v26, vcc, s18, v42
	global_load_dwordx4 v[2:5], v[6:7], off offset:16
	s_nop 0
	global_load_dwordx4 v[6:9], v[6:7], off
	v_addc_co_u32_e32 v27, vcc, 0, v43, vcc
	v_add_co_u32_e32 v34, vcc, s19, v42
	global_load_dwordx4 v[10:13], v[42:43], off
	s_nop 0
	global_load_dwordx4 v[14:17], v[14:15], off
	v_addc_co_u32_e32 v35, vcc, 0, v43, vcc
	v_add_co_u32_e32 v38, vcc, 0xdc000, v42
	global_load_dwordx4 v[22:25], v[22:23], off
	s_nop 0
	global_load_dwordx4 v[26:29], v[26:27], off
	v_addc_co_u32_e32 v39, vcc, 0, v43, vcc
	v_add_co_u32_e32 v44, vcc, 0x108000, v42
	global_load_dwordx4 v[34:37], v[34:35], off
	s_nop 0
	global_load_dwordx4 v[38:41], v[38:39], off
	v_addc_co_u32_e32 v45, vcc, 0, v43, vcc
	v_add_co_u32_e32 v46, vcc, 0x134000, v42
	s_add_i32 s6, s25, s28
	s_nop 0
	v_addc_co_u32_e32 v47, vcc, 0, v43, vcc
	global_load_dwordx4 v[42:45], v[44:45], off
	s_nop 0
	global_load_dwordx4 v[46:49], v[46:47], off
	s_cmpk_gt_i32 s6, 0xaff
	s_cbranch_scc1 .LBB0_797
; #define LAS __attribute__((address_space(3)))
; __device__ __forceinline__ unsigned cvtpk(float lo, float hi) { f32x2_t v = {lo, hi}; bf16x2_t b = __builtin_convertvector(v, bf16x2_t); return __builtin_bit_cast(unsigned, b); }
; #define LDS_WAIT() asm volatile("s_waitcnt lgkmcnt(0)" ::: "memory")
; __device__ __forceinline__ void conv_emit(const ConvJob& j, int lane, const ConvSet& s, LAS float* scr) {
;     const int k0 = 64 * j.kb; int cnt; (void)vgroup_src(j.kind, j.g, cnt);
;     const int ks = lane >> 3, n4 = (lane & 7) * 4, c = lane & 7; const bool okc = n4 < cnt;
;     const f32x4 one = (f32x4){1.f, 1.f, 1.f, 1.f}; const f32x4 g0 = j.gain ? s.g0 : one, g1 = j.gain ? s.g1 : one;
; #pragma unroll
;     for (int i = 0; i < 8; ++i) { LAS float* sp = scr + (8 * i + ks) * 33 + n4;
; #pragma unroll
;         for (int e = 0; e < 4; ++e) sp[e] = okc ? s.v[i][e] : 0.f; }
;     LDS_WAIT(); asm volatile("" ::: "memory");
; #pragma unroll
;     for (int q = 0; q < 4; ++q) { const int nn = (lane >> 3) + 8 * q; const LAS float* sr = scr + (8 * c) * 33 + nn;
;         u32x4 o; o.x = cvtpk(sr[0 * 33] * g0[0], sr[1 * 33] * g0[1]); o.y = cvtpk(sr[2 * 33] * g0[2], sr[3 * 33] * g0[3]); o.z = cvtpk(sr[4 * 33] * g1[0], sr[5 * 33] * g1[1]); o.w = cvtpk(sr[6 * 33] * g1[2], sr[7 * 33] * g1[3]);
;         *(u32x4*)(j.WT + (size_t)(j.g * 32 + nn) * j.K + k0 + 8 * c) = o; }
	s_waitcnt vmcnt(31)
	ds_write2_b32 v135, v50, v51 offset1:1
	ds_write2_b32 v135, v52, v53 offset0:2 offset1:3
	s_waitcnt vmcnt(30)
	ds_write2_b32 v136, v54, v55 offset1:1
	ds_write2_b32 v137, v56, v57 offset1:1
	s_waitcnt vmcnt(29)
	ds_write2_b32 v138, v58, v59 offset1:1
	ds_write2_b32 v139, v60, v61 offset1:1
	s_waitcnt vmcnt(28)
	ds_write2_b32 v140, v62, v63 offset1:1
	ds_write2_b32 v141, v64, v65 offset1:1
	s_waitcnt vmcnt(27)
	ds_write2_b32 v142, v66, v67 offset1:1
	ds_write2_b32 v143, v68, v69 offset1:1
	s_waitcnt vmcnt(26)
	ds_write2_b32 v144, v70, v71 offset1:1
	ds_write2_b32 v145, v72, v73 offset1:1
	s_waitcnt vmcnt(25)
	ds_write2_b32 v146, v74, v75 offset1:1
	ds_write2_b32 v147, v76, v77 offset1:1
	s_waitcnt vmcnt(24)
	ds_write2_b32 v148, v78, v79 offset1:1
	ds_write2_b32 v149, v80, v81 offset1:1
	s_waitcnt lgkmcnt(0)
	ds_read2_b32 v[52:53], v134 offset1:8
	ds_read2_b32 v[56:57], v134 offset0:33 offset1:41
	ds_read2_b32 v[58:59], v134 offset0:66 offset1:74
	ds_read2_b32 v[60:61], v134 offset0:99 offset1:107
	ds_read2_b32 v[62:63], v134 offset0:132 offset1:140
	ds_read2_b32 v[64:65], v134 offset0:165 offset1:173
	ds_read2_b32 v[66:67], v134 offset0:198 offset1:206
	ds_read2_b32 v[68:69], v134 offset0:231 offset1:239
	s_mul_hi_i32 s7, s6, 0x2e8ba2e9
	s_lshr_b32 s30, s7, 31
	s_ashr_i32 s7, s7, 5
	s_add_i32 s7, s7, s30
	v_cndmask_b32_e64 v33, v33, 1.0, s[0:1]
	v_cndmask_b32_e64 v32, v32, 1.0, s[0:1]
	v_cndmask_b32_e64 v31, v31, 1.0, s[0:1]
	v_cndmask_b32_e64 v30, v30, 1.0, s[0:1]
	v_cndmask_b32_e64 v51, v21, 1.0, s[0:1]
	v_cndmask_b32_e64 v50, v20, 1.0, s[0:1]
	v_cndmask_b32_e64 v55, v19, 1.0, s[0:1]
	v_cndmask_b32_e64 v54, v18, 1.0, s[0:1]
	s_waitcnt lgkmcnt(7)
	v_mov_b32_e32 v18, v52
	s_waitcnt lgkmcnt(6)
	v_mov_b32_e32 v19, v56
	s_waitcnt lgkmcnt(5)
	v_mov_b32_e32 v20, v58
	s_waitcnt lgkmcnt(4)
	v_mov_b32_e32 v21, v60
	s_mul_i32 s30, s7, 0xb0
	v_pk_mul_f32 v[18:19], v[30:31], v[18:19]
	v_pk_mul_f32 v[20:21], v[32:33], v[20:21]
	s_sub_i32 s30, s6, s30
	v_cvt_pk_bf16_f32 v18, v18, v19
	v_cvt_pk_bf16_f32 v19, v20, v21
	s_waitcnt lgkmcnt(3)
	v_mov_b32_e32 v20, v62
	s_waitcnt lgkmcnt(2)
	v_mov_b32_e32 v21, v64
	s_waitcnt lgkmcnt(1)
	v_mov_b32_e32 v70, v66
	s_waitcnt lgkmcnt(0)
	v_mov_b32_e32 v71, v68
	v_pk_mul_f32 v[20:21], v[54:55], v[20:21]
	v_pk_mul_f32 v[70:71], v[50:51], v[70:71]
	s_lshl_b32 s30, s30, 5
	v_cvt_pk_bf16_f32 v20, v20, v21
	v_cvt_pk_bf16_f32 v21, v70, v71
	v_or_b32_e32 v70, s30, v130
	s_lshl_b32 s6, s7, 6
	v_ashrrev_i32_e32 v71, 31, v70
	v_readlane_b32 s34, v252, 9
	s_ashr_i32 s7, s6, 31
	v_lshlrev_b64 v[70:71], 11, v[70:71]
	v_readlane_b32 s35, v252, 10
	s_lshl_b64 s[6:7], s[6:7], 1
	v_mov_b32_e32 v56, v53
	v_lshl_add_u64 v[70:71], s[34:35], 0, v[70:71]
	v_lshl_add_u64 v[70:71], v[70:71], 0, s[6:7]
	v_lshl_add_u64 v[70:71], v[70:71], 0, v[126:127]
	v_mov_b32_e32 v60, v59
	global_store_dwordx4 v[70:71], v[18:21], off sc1
	v_mov_b32_e32 v64, v63
	v_mov_b32_e32 v68, v67
	v_pk_mul_f32 v[18:19], v[30:31], v[56:57]
	v_pk_mul_f32 v[20:21], v[32:33], v[60:61]
	v_cvt_pk_bf16_f32 v18, v18, v19
	v_cvt_pk_bf16_f32 v19, v20, v21
	v_pk_mul_f32 v[20:21], v[54:55], v[64:65]
	v_pk_mul_f32 v[52:53], v[50:51], v[68:69]
	v_cvt_pk_bf16_f32 v20, v20, v21
	v_cvt_pk_bf16_f32 v21, v52, v53
	v_or_b32_e32 v52, s30, v131
	v_ashrrev_i32_e32 v53, 31, v52
	v_lshlrev_b64 v[52:53], 11, v[52:53]
	v_lshl_add_u64 v[52:53], s[34:35], 0, v[52:53]
	v_lshl_add_u64 v[52:53], v[52:53], 0, s[6:7]
	v_lshl_add_u64 v[52:53], v[52:53], 0, v[126:127]
	ds_read2_b32 v[56:57], v134 offset0:16 offset1:24
	ds_read2_b32 v[58:59], v134 offset0:49 offset1:57
	global_store_dwordx4 v[52:53], v[18:21], off sc1
	ds_read2_b32 v[52:53], v134 offset0:82 offset1:90
	ds_read2_b32 v[60:61], v134 offset0:115 offset1:123
	ds_read2_b32 v[62:63], v134 offset0:148 offset1:156
	ds_read2_b32 v[64:65], v134 offset0:181 offset1:189
	ds_read2_b32 v[66:67], v134 offset0:214 offset1:222
	ds_read2_b32 v[68:69], v134 offset0:247 offset1:255
	s_waitcnt lgkmcnt(7)
	v_mov_b32_e32 v18, v56
	s_waitcnt lgkmcnt(6)
	v_mov_b32_e32 v19, v58
	s_waitcnt lgkmcnt(5)
	v_mov_b32_e32 v20, v52
	s_waitcnt lgkmcnt(4)
	v_mov_b32_e32 v21, v60
	v_pk_mul_f32 v[18:19], v[30:31], v[18:19]
	v_pk_mul_f32 v[20:21], v[32:33], v[20:21]
	v_cvt_pk_bf16_f32 v18, v18, v19
	v_cvt_pk_bf16_f32 v19, v20, v21
	s_waitcnt lgkmcnt(3)
	v_mov_b32_e32 v20, v62
	s_waitcnt lgkmcnt(2)
	v_mov_b32_e32 v21, v64
	s_waitcnt lgkmcnt(1)
	v_mov_b32_e32 v70, v66
	s_waitcnt lgkmcnt(0)
	v_mov_b32_e32 v71, v68
	v_pk_mul_f32 v[20:21], v[54:55], v[20:21]
	v_pk_mul_f32 v[70:71], v[50:51], v[70:71]
	v_cvt_pk_bf16_f32 v20, v20, v21
	v_cvt_pk_bf16_f32 v21, v70, v71
	v_or_b32_e32 v70, s30, v132
	v_ashrrev_i32_e32 v71, 31, v70
	v_lshlrev_b64 v[70:71], 11, v[70:71]
	v_lshl_add_u64 v[70:71], s[34:35], 0, v[70:71]
	v_lshl_add_u64 v[70:71], v[70:71], 0, s[6:7]
	v_lshl_add_u64 v[70:71], v[70:71], 0, v[126:127]
	v_mov_b32_e32 v58, v57
	v_mov_b32_e32 v60, v53
	global_store_dwordx4 v[70:71], v[18:21], off sc1
	v_mov_b32_e32 v64, v63
	v_mov_b32_e32 v68, v67
	v_pk_mul_f32 v[18:19], v[30:31], v[58:59]
	v_pk_mul_f32 v[20:21], v[32:33], v[60:61]
	v_cvt_pk_bf16_f32 v18, v18, v19
	v_cvt_pk_bf16_f32 v19, v20, v21
	v_pk_mul_f32 v[20:21], v[54:55], v[64:65]
	v_pk_mul_f32 v[30:31], v[50:51], v[68:69]
	v_cvt_pk_bf16_f32 v20, v20, v21
	v_cvt_pk_bf16_f32 v21, v30, v31
	v_or_b32_e32 v30, s30, v133
	v_ashrrev_i32_e32 v31, 31, v30
	v_lshlrev_b64 v[30:31], 11, v[30:31]
	v_lshl_add_u64 v[30:31], s[34:35], 0, v[30:31]
	v_lshl_add_u64 v[30:31], v[30:31], 0, s[6:7]
	v_lshl_add_u64 v[30:31], v[30:31], 0, v[126:127]
	global_store_dwordx4 v[30:31], v[18:21], off sc1
	s_waitcnt lgkmcnt(0)
; __device__ __forceinline__ int vgroup_src(int kind, int g, int& cnt) {
;     cnt = 32;
;     if (kind == 0) return g * 32;
;     if (kind == 1) { const int pn = g >> 3, tg = g & 7; return (tg >> 2) * FF + pn * 128 + (tg & 3) * 32; }
; __device__ __forceinline__ void conv_fetch(const ConvJob& j, int lane, ConvSet& s) {
;     const int k0 = 64 * j.kb; int cnt; const int src = vgroup_src(j.kind, j.g, cnt);
;     const int ks = lane >> 3, n4 = (lane & 7) * 4, c = lane & 7; const bool okc = n4 < cnt;
;     const float* gp = j.gain ? j.gain + k0 + 8 * c : j.W;
;     s.g0 = *(const f32x4*)gp; s.g1 = *(const f32x4*)(gp + 4);
;     const float* wp = j.W + (size_t)(k0 + ks) * j.Norig + src + (okc ? n4 : 0);
; #pragma unroll
;     for (int i = 0; i < 8; ++i) s.v[i] = *(const f32x4*)(wp + (size_t)(8 * i) * j.Norig);
; }
.LBB0_797:
	s_add_i32 s6, s26, s28
	s_min_i32 s6, s6, 0xaff
	s_mul_hi_i32 s7, s6, 0x2e8ba2e9
	s_lshr_b32 s30, s7, 31
	s_ashr_i32 s7, s7, 5
	s_add_i32 s7, s7, s30
	s_mul_i32 s30, s7, 0xb0
	s_sub_i32 s30, s6, s30
	s_lshl_b32 s6, s7, 6
	s_bfe_i32 s7, s30, 0x10002
	s_lshl_b32 s31, s30, 4
	s_and_b32 s7, s7, 0xb00
	s_and_b32 s31, s31, 0xffffff80
	s_lshl_b32 s30, s30, 5
	s_add_i32 s7, s7, s31
	s_and_b32 s30, s30, 0x60
	s_or_b32 s30, s7, s30
	s_ashr_i32 s7, s6, 31
	s_waitcnt vmcnt(31)
	v_or_b32_e32 v52, s6, v130
	v_mov_b64_e32 v[50:51], s[44:45]
	v_lshl_add_u64 v[18:19], s[6:7], 2, v[124:125]
	v_mad_i64_i32 v[50:51], s[6:7], v52, s9, v[50:51]
	s_ashr_i32 s31, s30, 31
	v_lshl_add_u64 v[50:51], s[30:31], 2, v[50:51]
	s_waitcnt vmcnt(25)
	v_lshl_add_u64 v[74:75], v[50:51], 0, v[122:123]
	v_add_co_u32_e32 v54, vcc, s10, v74
	v_mov_b32_e32 v20, s45
	s_nop 0
	v_addc_co_u32_e32 v55, vcc, 0, v75, vcc
	v_add_co_u32_e32 v58, vcc, s11, v74
	v_cndmask_b32_e64 v31, v19, v20, s[0:1]
	s_nop 0
	v_addc_co_u32_e32 v59, vcc, 0, v75, vcc
	v_add_co_u32_e32 v62, vcc, s18, v74
	v_mov_b32_e32 v19, s44
	s_nop 0
	v_addc_co_u32_e32 v63, vcc, 0, v75, vcc
	v_add_co_u32_e32 v66, vcc, s19, v74
	v_cndmask_b32_e64 v30, v18, v19, s[0:1]
	s_nop 0
	v_addc_co_u32_e32 v67, vcc, 0, v75, vcc
	v_add_co_u32_e32 v70, vcc, 0xdc000, v74
	global_load_dwordx4 v[18:21], v[30:31], off offset:16
	s_nop 0
	global_load_dwordx4 v[30:33], v[30:31], off
	v_addc_co_u32_e32 v71, vcc, 0, v75, vcc
	v_add_co_u32_e32 v76, vcc, 0x108000, v74
	global_load_dwordx4 v[50:53], v[74:75], off
	s_nop 0
	global_load_dwordx4 v[54:57], v[54:55], off
	v_addc_co_u32_e32 v77, vcc, 0, v75, vcc
	s_waitcnt vmcnt(28)
	v_add_co_u32_e32 v78, vcc, 0x134000, v74
	global_load_dwordx4 v[58:61], v[58:59], off
	s_nop 0
	global_load_dwordx4 v[62:65], v[62:63], off
	v_addc_co_u32_e32 v79, vcc, 0, v75, vcc
	global_load_dwordx4 v[66:69], v[66:67], off
	s_nop 0
	global_load_dwordx4 v[70:73], v[70:71], off
	s_nop 0
	global_load_dwordx4 v[74:77], v[76:77], off
	s_nop 0
	global_load_dwordx4 v[78:81], v[78:79], off
	s_andn2_b64 vcc, exec, s[4:5]
	s_cbranch_vccnz .LBB0_794
; #define LAS __attribute__((address_space(3)))
; __device__ __forceinline__ unsigned cvtpk(float lo, float hi) { f32x2_t v = {lo, hi}; bf16x2_t b = __builtin_convertvector(v, bf16x2_t); return __builtin_bit_cast(unsigned, b); }
; #define LDS_WAIT() asm volatile("s_waitcnt lgkmcnt(0)" ::: "memory")
; __device__ __forceinline__ void conv_emit(const ConvJob& j, int lane, const ConvSet& s, LAS float* scr) {
;     const int k0 = 64 * j.kb; int cnt; (void)vgroup_src(j.kind, j.g, cnt);
;     const int ks = lane >> 3, n4 = (lane & 7) * 4, c = lane & 7; const bool okc = n4 < cnt;
;     const f32x4 one = (f32x4){1.f, 1.f, 1.f, 1.f}; const f32x4 g0 = j.gain ? s.g0 : one, g1 = j.gain ? s.g1 : one;
; #pragma unroll
;     for (int i = 0; i < 8; ++i) { LAS float* sp = scr + (8 * i + ks) * 33 + n4;
; #pragma unroll
;         for (int e = 0; e < 4; ++e) sp[e] = okc ? s.v[i][e] : 0.f; }
;     LDS_WAIT(); asm volatile("" ::: "memory");
; #pragma unroll
;     for (int q = 0; q < 4; ++q) { const int nn = (lane >> 3) + 8 * q; const LAS float* sr = scr + (8 * c) * 33 + nn;
;         u32x4 o; o.x = cvtpk(sr[0 * 33] * g0[0], sr[1 * 33] * g0[1]); o.y = cvtpk(sr[2 * 33] * g0[2], sr[3 * 33] * g0[3]); o.z = cvtpk(sr[4 * 33] * g1[0], sr[5 * 33] * g1[1]); o.w = cvtpk(sr[6 * 33] * g1[2], sr[7 * 33] * g1[3]);
;         *(u32x4*)(j.WT + (size_t)(j.g * 32 + nn) * j.K + k0 + 8 * c) = o; }
	s_waitcnt vmcnt(31)
	ds_write2_b32 v135, v90, v91 offset1:1
	ds_write2_b32 v135, v92, v93 offset0:2 offset1:3
	s_waitcnt vmcnt(30)
	ds_write2_b32 v136, v94, v95 offset1:1
	ds_write2_b32 v137, v96, v97 offset1:1
	s_waitcnt vmcnt(29)
	ds_write2_b32 v138, v98, v99 offset1:1
	ds_write2_b32 v139, v100, v101 offset1:1
	s_waitcnt vmcnt(28)
	ds_write2_b32 v140, v102, v103 offset1:1
	ds_write2_b32 v141, v104, v105 offset1:1
	s_waitcnt vmcnt(27)
	ds_write2_b32 v142, v106, v107 offset1:1
	ds_write2_b32 v143, v108, v109 offset1:1
	s_waitcnt vmcnt(26)
	ds_write2_b32 v144, v110, v111 offset1:1
	ds_write2_b32 v145, v112, v113 offset1:1
	s_waitcnt vmcnt(25)
	ds_write2_b32 v146, v114, v115 offset1:1
	ds_write2_b32 v147, v116, v117 offset1:1
	s_waitcnt vmcnt(24)
	ds_write2_b32 v148, v118, v119 offset1:1
	ds_write2_b32 v149, v120, v121 offset1:1
	s_waitcnt lgkmcnt(0)
	ds_read2_b32 v[92:93], v134 offset1:8
	ds_read2_b32 v[96:97], v134 offset0:33 offset1:41
	ds_read2_b32 v[98:99], v134 offset0:66 offset1:74
	ds_read2_b32 v[100:101], v134 offset0:99 offset1:107
	ds_read2_b32 v[102:103], v134 offset0:132 offset1:140
	ds_read2_b32 v[104:105], v134 offset0:165 offset1:173
	ds_read2_b32 v[106:107], v134 offset0:198 offset1:206
	ds_read2_b32 v[108:109], v134 offset0:231 offset1:239
	s_mul_hi_i32 s4, s29, 0x2e8ba2e9
	s_lshr_b32 s5, s4, 31
	s_ashr_i32 s4, s4, 5
	s_add_i32 s4, s4, s5
	v_cndmask_b32_e64 v89, v89, 1.0, s[0:1]
	v_cndmask_b32_e64 v88, v88, 1.0, s[0:1]
	v_cndmask_b32_e64 v87, v87, 1.0, s[0:1]
	v_cndmask_b32_e64 v86, v86, 1.0, s[0:1]
	v_cndmask_b32_e64 v91, v85, 1.0, s[0:1]
	v_cndmask_b32_e64 v90, v84, 1.0, s[0:1]
	v_cndmask_b32_e64 v95, v83, 1.0, s[0:1]
	v_cndmask_b32_e64 v94, v82, 1.0, s[0:1]
	s_waitcnt lgkmcnt(7)
	v_mov_b32_e32 v82, v92
	s_waitcnt lgkmcnt(6)
	v_mov_b32_e32 v83, v96
	s_waitcnt lgkmcnt(5)
	v_mov_b32_e32 v84, v98
	s_waitcnt lgkmcnt(4)
	v_mov_b32_e32 v85, v100
	s_mul_i32 s5, s4, 0xb0
	v_pk_mul_f32 v[82:83], v[86:87], v[82:83]
	v_pk_mul_f32 v[84:85], v[88:89], v[84:85]
	s_sub_i32 s6, s29, s5
	v_cvt_pk_bf16_f32 v82, v82, v83
	v_cvt_pk_bf16_f32 v83, v84, v85
	s_waitcnt lgkmcnt(3)
	v_mov_b32_e32 v84, v102
	s_waitcnt lgkmcnt(2)
	v_mov_b32_e32 v85, v104
	s_waitcnt lgkmcnt(1)
	v_mov_b32_e32 v110, v106
	s_waitcnt lgkmcnt(0)
	v_mov_b32_e32 v111, v108
	v_pk_mul_f32 v[84:85], v[94:95], v[84:85]
	v_pk_mul_f32 v[110:111], v[90:91], v[110:111]
	s_lshl_b32 s6, s6, 5
	v_cvt_pk_bf16_f32 v84, v84, v85
	v_cvt_pk_bf16_f32 v85, v110, v111
	v_or_b32_e32 v110, s6, v130
	s_lshl_b32 s4, s4, 6
	v_ashrrev_i32_e32 v111, 31, v110
	v_readlane_b32 s30, v252, 9
	s_ashr_i32 s5, s4, 31
	v_lshlrev_b64 v[110:111], 11, v[110:111]
	v_readlane_b32 s31, v252, 10
	s_lshl_b64 s[4:5], s[4:5], 1
	v_mov_b32_e32 v127, v123
	v_lshl_add_u64 v[110:111], s[30:31], 0, v[110:111]
	v_lshl_add_u64 v[110:111], v[110:111], 0, s[4:5]
	v_lshl_add_u64 v[110:111], v[110:111], 0, v[126:127]
	v_mov_b32_e32 v96, v93
	v_mov_b32_e32 v100, v99
	global_store_dwordx4 v[110:111], v[82:85], off sc1
	v_mov_b32_e32 v104, v103
	v_mov_b32_e32 v108, v107
	v_pk_mul_f32 v[82:83], v[86:87], v[96:97]
	v_pk_mul_f32 v[84:85], v[88:89], v[100:101]
	v_cvt_pk_bf16_f32 v82, v82, v83
	v_cvt_pk_bf16_f32 v83, v84, v85
	v_pk_mul_f32 v[84:85], v[94:95], v[104:105]
	v_pk_mul_f32 v[92:93], v[90:91], v[108:109]
	v_cvt_pk_bf16_f32 v84, v84, v85
	v_cvt_pk_bf16_f32 v85, v92, v93
	v_or_b32_e32 v92, s6, v131
	v_ashrrev_i32_e32 v93, 31, v92
	v_lshlrev_b64 v[92:93], 11, v[92:93]
	v_lshl_add_u64 v[92:93], s[30:31], 0, v[92:93]
	v_lshl_add_u64 v[92:93], v[92:93], 0, s[4:5]
	v_lshl_add_u64 v[92:93], v[92:93], 0, v[126:127]
	ds_read2_b32 v[96:97], v134 offset0:16 offset1:24
	ds_read2_b32 v[98:99], v134 offset0:49 offset1:57
	global_store_dwordx4 v[92:93], v[82:85], off sc1
	ds_read2_b32 v[92:93], v134 offset0:82 offset1:90
	ds_read2_b32 v[100:101], v134 offset0:115 offset1:123
	ds_read2_b32 v[102:103], v134 offset0:148 offset1:156
	ds_read2_b32 v[104:105], v134 offset0:181 offset1:189
	ds_read2_b32 v[106:107], v134 offset0:214 offset1:222
	ds_read2_b32 v[108:109], v134 offset0:247 offset1:255
	s_waitcnt lgkmcnt(7)
	v_mov_b32_e32 v82, v96
	s_waitcnt lgkmcnt(6)
	v_mov_b32_e32 v83, v98
	s_waitcnt lgkmcnt(5)
	v_mov_b32_e32 v84, v92
	s_waitcnt lgkmcnt(4)
	v_mov_b32_e32 v85, v100
	v_pk_mul_f32 v[82:83], v[86:87], v[82:83]
	v_pk_mul_f32 v[84:85], v[88:89], v[84:85]
	v_cvt_pk_bf16_f32 v82, v82, v83
	v_cvt_pk_bf16_f32 v83, v84, v85
	s_waitcnt lgkmcnt(3)
	v_mov_b32_e32 v84, v102
	s_waitcnt lgkmcnt(2)
	v_mov_b32_e32 v85, v104
	s_waitcnt lgkmcnt(1)
	v_mov_b32_e32 v110, v106
	s_waitcnt lgkmcnt(0)
	v_mov_b32_e32 v111, v108
	v_pk_mul_f32 v[84:85], v[94:95], v[84:85]
	v_pk_mul_f32 v[110:111], v[90:91], v[110:111]
	v_cvt_pk_bf16_f32 v84, v84, v85
	v_cvt_pk_bf16_f32 v85, v110, v111
	v_or_b32_e32 v110, s6, v132
	v_ashrrev_i32_e32 v111, 31, v110
	v_lshlrev_b64 v[110:111], 11, v[110:111]
	v_lshl_add_u64 v[110:111], s[30:31], 0, v[110:111]
	v_lshl_add_u64 v[110:111], v[110:111], 0, s[4:5]
	v_lshl_add_u64 v[110:111], v[110:111], 0, v[126:127]
	v_mov_b32_e32 v98, v97
	v_mov_b32_e32 v100, v93
	global_store_dwordx4 v[110:111], v[82:85], off sc1
	v_mov_b32_e32 v104, v103
	v_mov_b32_e32 v108, v107
	v_pk_mul_f32 v[82:83], v[86:87], v[98:99]
	v_pk_mul_f32 v[84:85], v[88:89], v[100:101]
	v_cvt_pk_bf16_f32 v82, v82, v83
	v_cvt_pk_bf16_f32 v83, v84, v85
	v_pk_mul_f32 v[84:85], v[94:95], v[104:105]
	v_pk_mul_f32 v[86:87], v[90:91], v[108:109]
	v_cvt_pk_bf16_f32 v84, v84, v85
	v_cvt_pk_bf16_f32 v85, v86, v87
	v_or_b32_e32 v86, s6, v133
	v_ashrrev_i32_e32 v87, 31, v86
	v_lshlrev_b64 v[86:87], 11, v[86:87]
	v_lshl_add_u64 v[86:87], s[30:31], 0, v[86:87]
	v_lshl_add_u64 v[86:87], v[86:87], 0, s[4:5]
	v_lshl_add_u64 v[86:87], v[86:87], 0, v[126:127]
	global_store_dwordx4 v[86:87], v[82:85], off sc1
	s_waitcnt lgkmcnt(0)
	s_branch .LBB0_794

; #define LAS __attribute__((address_space(3)))
; __device__ __forceinline__ unsigned cvtpk(float lo, float hi) { f32x2_t v = {lo, hi}; bf16x2_t b = __builtin_convertvector(v, bf16x2_t); return __builtin_bit_cast(unsigned, b); }
; #define LDS_WAIT() asm volatile("s_waitcnt lgkmcnt(0)" ::: "memory")
; __device__ __forceinline__ void conv_fetch(const ConvJob& j, int lane, ConvSet& s) {
;     const int k0 = 64 * j.kb; int cnt; const int src = vgroup_src(j.kind, j.g, cnt);
;     const int ks = lane >> 3, n4 = (lane & 7) * 4, c = lane & 7; const bool okc = n4 < cnt;
;     const float* gp = j.gain ? j.gain + k0 + 8 * c : j.W;
;     s.g0 = *(const f32x4*)gp; s.g1 = *(const f32x4*)(gp + 4);
;     const float* wp = j.W + (size_t)(k0 + ks) * j.Norig + src + (okc ? n4 : 0);
; #pragma unroll
;     for (int i = 0; i < 8; ++i) s.v[i] = *(const f32x4*)(wp + (size_t)(8 * i) * j.Norig);
; }
; __device__ __forceinline__ void conv_emit(const ConvJob& j, int lane, const ConvSet& s, LAS float* scr) {
;     const int k0 = 64 * j.kb; int cnt; (void)vgroup_src(j.kind, j.g, cnt);
;     const int ks = lane >> 3, n4 = (lane & 7) * 4, c = lane & 7; const bool okc = n4 < cnt;
;     const f32x4 one = (f32x4){1.f, 1.f, 1.f, 1.f}; const f32x4 g0 = j.gain ? s.g0 : one, g1 = j.gain ? s.g1 : one;
; #pragma unroll
;     for (int i = 0; i < 8; ++i) { LAS float* sp = scr + (8 * i + ks) * 33 + n4;
; #pragma unroll
;         for (int e = 0; e < 4; ++e) sp[e] = okc ? s.v[i][e] : 0.f; }
;     LDS_WAIT(); asm volatile("" ::: "memory");
; #pragma unroll
;     for (int q = 0; q < 4; ++q) { const int nn = (lane >> 3) + 8 * q; const LAS float* sr = scr + (8 * c) * 33 + nn;
;         u32x4 o; o.x = cvtpk(sr[0 * 33] * g0[0], sr[1 * 33] * g0[1]); o.y = cvtpk(sr[2 * 33] * g0[2], sr[3 * 33] * g0[3]); o.z = cvtpk(sr[4 * 33] * g1[0], sr[5 * 33] * g1[1]); o.w = cvtpk(sr[6 * 33] * g1[2], sr[7 * 33] * g1[3]);
;         *(u32x4*)(j.WT + (size_t)(j.g * 32 + nn) * j.K + k0 + 8 * c) = o; }
.LBB0_1693:
	s_add_i32 s20, s11, s19
	s_cmpk_lt_i32 s20, 0x580
	s_cselect_b64 s[0:1], -1, 0
	s_and_b64 s[22:23], s[0:1], exec
	s_cselect_b32 s21, s20, 0x57f
	s_ashr_i32 s22, s21, 31
	s_lshr_b32 s22, s22, 27
	s_add_i32 s22, s21, s22
	s_and_b32 s23, s22, 0x7ffffe0
	s_lshl_b32 s22, s22, 1
	s_sub_i32 s21, s21, s23
	s_and_b32 s23, s22, 0xffffffc0
	s_waitcnt vmcnt(27)
	v_or_b32_e32 v66, s23, v102
	v_ashrrev_i32_e32 v67, 31, v66
	s_lshl_b32 s22, s21, 5
	v_lshlrev_b64 v[66:67], 12, v[66:67]
	v_lshl_add_u64 v[66:67], s[46:47], 0, v[66:67]
	s_ashr_i32 s23, s22, 31
	v_lshl_add_u64 v[66:67], s[22:23], 2, v[66:67]
	s_waitcnt vmcnt(20)
	v_lshl_add_u64 v[90:91], v[66:67], 0, v[98:99]
	v_add_co_u32_e32 v70, vcc, s4, v90
	s_ashr_i32 s21, s19, 31
	s_nop 0
	v_addc_co_u32_e32 v71, vcc, 0, v91, vcc
	v_add_co_u32_e32 v74, vcc, s5, v90
	global_load_dwordx4 v[66:69], v[90:91], off
	s_nop 0
	global_load_dwordx4 v[70:73], v[70:71], off
	v_addc_co_u32_e32 v75, vcc, 0, v91, vcc
	v_add_co_u32_e32 v78, vcc, s6, v90
	v_add_u32_e32 v109, 0x420, v108
	s_nop 0
	v_addc_co_u32_e32 v79, vcc, 0, v91, vcc
	v_add_co_u32_e32 v82, vcc, s7, v90
	v_add_u32_e32 v110, 0x428, v108
	s_nop 0
	v_addc_co_u32_e32 v83, vcc, 0, v91, vcc
	v_add_co_u32_e32 v86, vcc, s8, v90
	v_add_u32_e32 v111, 0x840, v108
	s_nop 0
	v_addc_co_u32_e32 v87, vcc, 0, v91, vcc
	v_add_co_u32_e32 v92, vcc, s9, v90
	v_add_u32_e32 v112, 0x848, v108
	s_nop 0
	v_addc_co_u32_e32 v93, vcc, 0, v91, vcc
	v_add_co_u32_e32 v90, vcc, s10, v90
	v_add_u32_e32 v113, 0xc60, v108
	s_nop 0
	v_addc_co_u32_e32 v91, vcc, 0, v91, vcc
	v_add_u32_e32 v114, 0xc68, v108
	v_add_u32_e32 v115, 0x1080, v108
	v_add_u32_e32 v116, 0x1088, v108
	v_add_u32_e32 v117, 0x14a0, v108
	v_add_u32_e32 v118, 0x14a8, v108
	v_add_u32_e32 v119, 0x18c0, v108
	v_add_u32_e32 v120, 0x18c8, v108
	v_add_u32_e32 v121, 0x1ce0, v108
	v_add_u32_e32 v122, 0x1ce8, v108
	global_load_dwordx4 v[74:77], v[74:75], off
	s_nop 0
	global_load_dwordx4 v[78:81], v[78:79], off
	s_nop 0
	global_load_dwordx4 v[82:85], v[82:83], off
	s_nop 0
	global_load_dwordx4 v[86:89], v[86:87], off
	s_nop 0
	global_load_dwordx4 v[94:97], v[92:93], off
	s_nop 0
	global_load_dwordx4 v[90:93], v[90:91], off
	s_lshr_b32 s21, s21, 27
	s_waitcnt vmcnt(23)
	ds_write2_b32 v108, v2, v3 offset1:1
	ds_write2_b32 v108, v4, v5 offset0:2 offset1:3
	s_waitcnt vmcnt(22)
	ds_write2_b32 v109, v6, v7 offset1:1
	ds_write2_b32 v110, v8, v9 offset1:1
	s_waitcnt vmcnt(21)
	ds_write2_b32 v111, v10, v11 offset1:1
	ds_write2_b32 v112, v12, v13 offset1:1
	s_waitcnt vmcnt(20)
	ds_write2_b32 v113, v14, v15 offset1:1
	ds_write2_b32 v114, v16, v17 offset1:1
	s_waitcnt vmcnt(19)
	ds_write2_b32 v115, v18, v19 offset1:1
	ds_write2_b32 v116, v20, v21 offset1:1
	s_waitcnt vmcnt(18)
	ds_write2_b32 v117, v22, v23 offset1:1
	ds_write2_b32 v118, v24, v25 offset1:1
	s_waitcnt vmcnt(17)
	ds_write2_b32 v119, v26, v27 offset1:1
	ds_write2_b32 v120, v28, v29 offset1:1
	s_waitcnt vmcnt(16)
	ds_write2_b32 v121, v30, v31 offset1:1
	ds_write2_b32 v122, v32, v33 offset1:1
	s_add_i32 s21, s19, s21
	s_waitcnt lgkmcnt(0)
	s_ashr_i32 s21, s21, 5
	s_lshl_b32 s22, s21, 6
	ds_read2_b32 v[6:7], v106 offset0:33 offset1:41
	ds_read2_b32 v[8:9], v106 offset1:8
	ds_read2_b32 v[10:11], v106 offset0:66 offset1:74
	ds_read2_b32 v[12:13], v106 offset0:99 offset1:107
	ds_read2_b32 v[14:15], v106 offset0:132 offset1:140
	ds_read2_b32 v[16:17], v106 offset0:165 offset1:173
	ds_read2_b32 v[18:19], v106 offset0:198 offset1:206
	ds_read2_b32 v[20:21], v106 offset0:231 offset1:239
	s_mul_i32 s21, s21, 0xffa80000
	v_add_u32_e32 v22, s21, v107
	s_ashr_i32 s23, s22, 31
	v_ashrrev_i32_e32 v23, 31, v22
	v_lshl_add_u64 v[24:25], s[78:79], 0, v[22:23]
	s_lshl_b64 s[22:23], s[22:23], 1
	v_lshl_add_u64 v[24:25], v[24:25], 0, s[22:23]
	v_mov_b32_e32 v101, v99
	s_waitcnt lgkmcnt(6)
	v_cvt_pk_bf16_f32 v2, v8, v6
	s_waitcnt lgkmcnt(4)
	v_cvt_pk_bf16_f32 v3, v10, v12
	s_waitcnt lgkmcnt(2)
	v_cvt_pk_bf16_f32 v4, v14, v16
	s_waitcnt lgkmcnt(0)
	v_cvt_pk_bf16_f32 v5, v18, v20
	v_lshl_add_u64 v[24:25], v[24:25], 0, v[100:101]
	v_add_u32_e32 v6, 0xb000, v22
	global_store_dwordx4 v[24:25], v[2:5], off sc1
	s_add_i32 s21, s19, s14
	s_nop 0
	v_cvt_pk_bf16_f32 v2, v9, v7
	v_ashrrev_i32_e32 v7, 31, v6
	v_lshl_add_u64 v[6:7], s[78:79], 0, v[6:7]
	v_lshl_add_u64 v[6:7], v[6:7], 0, s[22:23]
	v_cvt_pk_bf16_f32 v3, v11, v13
	v_cvt_pk_bf16_f32 v4, v15, v17
	v_cvt_pk_bf16_f32 v5, v19, v21
	v_lshl_add_u64 v[6:7], v[6:7], 0, v[100:101]
	ds_read2_b32 v[8:9], v106 offset0:49 offset1:57
	ds_read2_b32 v[10:11], v106 offset0:16 offset1:24
	ds_read2_b32 v[12:13], v106 offset0:82 offset1:90
	ds_read2_b32 v[14:15], v106 offset0:115 offset1:123
	ds_read2_b32 v[16:17], v106 offset0:148 offset1:156
	ds_read2_b32 v[18:19], v106 offset0:181 offset1:189
	ds_read2_b32 v[20:21], v106 offset0:214 offset1:222
	ds_read2_b32 v[24:25], v106 offset0:247 offset1:255
	global_store_dwordx4 v[6:7], v[2:5], off sc1
	v_add_u32_e32 v6, 0x16000, v22
	v_ashrrev_i32_e32 v7, 31, v6
	v_lshl_add_u64 v[6:7], s[78:79], 0, v[6:7]
	v_lshl_add_u64 v[6:7], v[6:7], 0, s[22:23]
	s_waitcnt lgkmcnt(6)
	v_cvt_pk_bf16_f32 v2, v10, v8
	s_waitcnt lgkmcnt(4)
	v_cvt_pk_bf16_f32 v3, v12, v14
	s_waitcnt lgkmcnt(2)
	v_cvt_pk_bf16_f32 v4, v16, v18
	s_waitcnt lgkmcnt(0)
; #define LAS __attribute__((address_space(3)))
; __device__ __forceinline__ unsigned cvtpk(float lo, float hi) { f32x2_t v = {lo, hi}; bf16x2_t b = __builtin_convertvector(v, bf16x2_t); return __builtin_bit_cast(unsigned, b); }
; #define LDS_WAIT() asm volatile("s_waitcnt lgkmcnt(0)" ::: "memory")
; __device__ __forceinline__ void conv_fetch(const ConvJob& j, int lane, ConvSet& s) {
;     const int k0 = 64 * j.kb; int cnt; const int src = vgroup_src(j.kind, j.g, cnt);
;     const int ks = lane >> 3, n4 = (lane & 7) * 4, c = lane & 7; const bool okc = n4 < cnt;
;     const float* gp = j.gain ? j.gain + k0 + 8 * c : j.W;
;     s.g0 = *(const f32x4*)gp; s.g1 = *(const f32x4*)(gp + 4);
;     const float* wp = j.W + (size_t)(k0 + ks) * j.Norig + src + (okc ? n4 : 0);
; #pragma unroll
;     for (int i = 0; i < 8; ++i) s.v[i] = *(const f32x4*)(wp + (size_t)(8 * i) * j.Norig);
; }
; __device__ __forceinline__ void conv_emit(const ConvJob& j, int lane, const ConvSet& s, LAS float* scr) {
;     const int k0 = 64 * j.kb; int cnt; (void)vgroup_src(j.kind, j.g, cnt);
;     const int ks = lane >> 3, n4 = (lane & 7) * 4, c = lane & 7; const bool okc = n4 < cnt;
;     const f32x4 one = (f32x4){1.f, 1.f, 1.f, 1.f}; const f32x4 g0 = j.gain ? s.g0 : one, g1 = j.gain ? s.g1 : one;
; #pragma unroll
;     for (int i = 0; i < 8; ++i) { LAS float* sp = scr + (8 * i + ks) * 33 + n4;
; #pragma unroll
;         for (int e = 0; e < 4; ++e) sp[e] = okc ? s.v[i][e] : 0.f; }
;     LDS_WAIT(); asm volatile("" ::: "memory");
; #pragma unroll
;     for (int q = 0; q < 4; ++q) { const int nn = (lane >> 3) + 8 * q; const LAS float* sr = scr + (8 * c) * 33 + nn;
;         u32x4 o; o.x = cvtpk(sr[0 * 33] * g0[0], sr[1 * 33] * g0[1]); o.y = cvtpk(sr[2 * 33] * g0[2], sr[3 * 33] * g0[3]); o.z = cvtpk(sr[4 * 33] * g1[0], sr[5 * 33] * g1[1]); o.w = cvtpk(sr[6 * 33] * g1[2], sr[7 * 33] * g1[3]);
;         *(u32x4*)(j.WT + (size_t)(j.g * 32 + nn) * j.K + k0 + 8 * c) = o; }
	v_cvt_pk_bf16_f32 v5, v20, v24
	v_lshl_add_u64 v[6:7], v[6:7], 0, v[100:101]
	global_store_dwordx4 v[6:7], v[2:5], off sc1
	v_add_u32_e32 v6, 0x21000, v22
	v_ashrrev_i32_e32 v7, 31, v6
	v_lshl_add_u64 v[6:7], s[78:79], 0, v[6:7]
	v_lshl_add_u64 v[6:7], v[6:7], 0, s[22:23]
	s_min_i32 s22, s21, 0x57f
	s_ashr_i32 s23, s22, 31
	s_lshr_b32 s23, s23, 27
	s_add_i32 s23, s22, s23
	s_and_b32 s24, s23, 0x7ffffe0
	s_lshl_b32 s23, s23, 1
	v_cvt_pk_bf16_f32 v2, v11, v9
	v_cvt_pk_bf16_f32 v3, v13, v15
	v_cvt_pk_bf16_f32 v4, v17, v19
	v_cvt_pk_bf16_f32 v5, v21, v25
	v_lshl_add_u64 v[6:7], v[6:7], 0, v[100:101]
	s_andn2_b32 s23, s23, 63
	global_store_dwordx4 v[6:7], v[2:5], off sc1
	s_sub_i32 s22, s22, s24
	s_lshl_b32 s22, s22, 5
	v_or_b32_e32 v2, s23, v102
	v_ashrrev_i32_e32 v3, 31, v2
	v_lshlrev_b64 v[2:3], 12, v[2:3]
	v_lshl_add_u64 v[2:3], s[46:47], 0, v[2:3]
	s_ashr_i32 s23, s22, 31
	v_lshl_add_u64 v[2:3], s[22:23], 2, v[2:3]
	v_lshl_add_u64 v[26:27], v[2:3], 0, v[98:99]
	v_add_co_u32_e32 v6, vcc, s4, v26
	s_waitcnt lgkmcnt(0)
	s_add_i32 s22, s17, s19
	s_nop 0
	v_addc_co_u32_e32 v7, vcc, 0, v27, vcc
	v_add_co_u32_e32 v10, vcc, s5, v26
	global_load_dwordx4 v[2:5], v[26:27], off
	s_nop 0
	global_load_dwordx4 v[6:9], v[6:7], off
	v_addc_co_u32_e32 v11, vcc, 0, v27, vcc
	v_add_co_u32_e32 v14, vcc, s6, v26
	s_cmpk_gt_i32 s22, 0x57f
	s_nop 0
	v_addc_co_u32_e32 v15, vcc, 0, v27, vcc
	v_add_co_u32_e32 v18, vcc, s7, v26
	global_load_dwordx4 v[10:13], v[10:11], off
	s_nop 0
	global_load_dwordx4 v[14:17], v[14:15], off
	v_addc_co_u32_e32 v19, vcc, 0, v27, vcc
	v_add_co_u32_e32 v22, vcc, 0x28000, v26
	s_nop 1
	v_addc_co_u32_e32 v23, vcc, 0, v27, vcc
	v_add_co_u32_e32 v28, vcc, 0x30000, v26
	global_load_dwordx4 v[18:21], v[18:19], off
	s_nop 0
	global_load_dwordx4 v[22:25], v[22:23], off
	v_addc_co_u32_e32 v29, vcc, 0, v27, vcc
	v_add_co_u32_e32 v30, vcc, 0x38000, v26
	s_nop 1
	v_addc_co_u32_e32 v31, vcc, 0, v27, vcc
	global_load_dwordx4 v[26:29], v[28:29], off
	s_nop 0
	global_load_dwordx4 v[30:33], v[30:31], off
	s_cbranch_scc1 .LBB0_1695
	s_ashr_i32 s23, s22, 31
	s_lshr_b32 s23, s23, 27
	s_add_i32 s23, s22, s23
	s_waitcnt vmcnt(27)
	ds_write2_b32 v108, v34, v35 offset1:1
	ds_write2_b32 v108, v36, v37 offset0:2 offset1:3
	s_waitcnt vmcnt(26)
	ds_write2_b32 v109, v38, v39 offset1:1
	ds_write2_b32 v110, v40, v41 offset1:1
	s_waitcnt vmcnt(25)
	ds_write2_b32 v111, v42, v43 offset1:1
	ds_write2_b32 v112, v44, v45 offset1:1
	s_waitcnt vmcnt(24)
	ds_write2_b32 v113, v46, v47 offset1:1
	ds_write2_b32 v114, v48, v49 offset1:1
	s_waitcnt vmcnt(23)
	ds_write2_b32 v115, v50, v51 offset1:1
	ds_write2_b32 v116, v52, v53 offset1:1
	s_waitcnt vmcnt(22)
	ds_write2_b32 v117, v54, v55 offset1:1
	ds_write2_b32 v118, v56, v57 offset1:1
	s_waitcnt vmcnt(21)
	ds_write2_b32 v119, v58, v59 offset1:1
	ds_write2_b32 v120, v60, v61 offset1:1
	s_waitcnt vmcnt(20)
	ds_write2_b32 v121, v62, v63 offset1:1
	ds_write2_b32 v122, v64, v65 offset1:1
	s_and_b32 s24, s23, 0x7ffffe0
	s_waitcnt lgkmcnt(0)
	s_sub_i32 s24, s22, s24
	ds_read2_b32 v[38:39], v106 offset0:33 offset1:41
	ds_read2_b32 v[40:41], v106 offset1:8
	ds_read2_b32 v[42:43], v106 offset0:66 offset1:74
	ds_read2_b32 v[44:45], v106 offset0:99 offset1:107
	ds_read2_b32 v[46:47], v106 offset0:132 offset1:140
	ds_read2_b32 v[48:49], v106 offset0:165 offset1:173
	ds_read2_b32 v[50:51], v106 offset0:198 offset1:206
	ds_read2_b32 v[52:53], v106 offset0:231 offset1:239
	s_lshl_b32 s24, s24, 5
	s_lshl_b32 s22, s23, 1
	s_waitcnt lgkmcnt(6)
	v_cvt_pk_bf16_f32 v34, v40, v38
	v_or_b32_e32 v38, s24, v102
	s_andn2_b32 s22, s22, 63
	v_mul_lo_u32 v54, v38, s15
	s_ashr_i32 s23, s22, 31
	v_ashrrev_i32_e32 v55, 31, v54
	v_lshl_add_u64 v[54:55], s[78:79], 0, v[54:55]
	s_lshl_b64 s[22:23], s[22:23], 1
	v_lshl_add_u64 v[54:55], v[54:55], 0, s[22:23]
	v_or_b32_e32 v38, s24, v103
	s_waitcnt lgkmcnt(4)
	v_cvt_pk_bf16_f32 v35, v42, v44
	s_waitcnt lgkmcnt(2)
	v_cvt_pk_bf16_f32 v36, v46, v48
	s_waitcnt lgkmcnt(0)
	v_cvt_pk_bf16_f32 v37, v50, v52
	v_lshl_add_u64 v[54:55], v[54:55], 0, v[100:101]
	v_mul_lo_u32 v38, v38, s15
	global_store_dwordx4 v[54:55], v[34:37], off sc1
	s_nop 1
	v_cvt_pk_bf16_f32 v34, v41, v39
	v_ashrrev_i32_e32 v39, 31, v38
	v_lshl_add_u64 v[38:39], s[78:79], 0, v[38:39]
	v_lshl_add_u64 v[38:39], v[38:39], 0, s[22:23]
	v_cvt_pk_bf16_f32 v35, v43, v45
	v_cvt_pk_bf16_f32 v36, v47, v49
	v_cvt_pk_bf16_f32 v37, v51, v53
	v_lshl_add_u64 v[38:39], v[38:39], 0, v[100:101]
	ds_read2_b32 v[40:41], v106 offset0:49 offset1:57
	ds_read2_b32 v[42:43], v106 offset0:16 offset1:24
	ds_read2_b32 v[44:45], v106 offset0:82 offset1:90
	ds_read2_b32 v[46:47], v106 offset0:115 offset1:123
	ds_read2_b32 v[48:49], v106 offset0:148 offset1:156
	ds_read2_b32 v[50:51], v106 offset0:181 offset1:189
	ds_read2_b32 v[52:53], v106 offset0:214 offset1:222
	ds_read2_b32 v[54:55], v106 offset0:247 offset1:255
	global_store_dwordx4 v[38:39], v[34:37], off sc1
	v_or_b32_e32 v38, s24, v104
	v_mul_lo_u32 v38, v38, s15
	v_ashrrev_i32_e32 v39, 31, v38
	v_lshl_add_u64 v[38:39], s[78:79], 0, v[38:39]
	v_lshl_add_u64 v[38:39], v[38:39], 0, s[22:23]
	s_waitcnt lgkmcnt(6)
	v_cvt_pk_bf16_f32 v34, v42, v40
	s_waitcnt lgkmcnt(4)
	v_cvt_pk_bf16_f32 v35, v44, v46
	s_waitcnt lgkmcnt(2)
	v_cvt_pk_bf16_f32 v36, v48, v50
	s_waitcnt lgkmcnt(0)
	v_cvt_pk_bf16_f32 v37, v52, v54
	v_lshl_add_u64 v[38:39], v[38:39], 0, v[100:101]
	global_store_dwordx4 v[38:39], v[34:37], off sc1
	v_or_b32_e32 v38, s24, v105
	v_mul_lo_u32 v38, v38, s15
	v_ashrrev_i32_e32 v39, 31, v38
	v_lshl_add_u64 v[38:39], s[78:79], 0, v[38:39]
	v_lshl_add_u64 v[38:39], v[38:39], 0, s[22:23]
	v_cvt_pk_bf16_f32 v34, v43, v41
	v_cvt_pk_bf16_f32 v35, v45, v47
	v_cvt_pk_bf16_f32 v36, v49, v51
	v_cvt_pk_bf16_f32 v37, v53, v55
	v_lshl_add_u64 v[38:39], v[38:39], 0, v[100:101]
	global_store_dwordx4 v[38:39], v[34:37], off sc1
	s_waitcnt lgkmcnt(0)
; #define LAS __attribute__((address_space(3)))
; __device__ __forceinline__ unsigned cvtpk(float lo, float hi) { f32x2_t v = {lo, hi}; bf16x2_t b = __builtin_convertvector(v, bf16x2_t); return __builtin_bit_cast(unsigned, b); }
; #define LDS_WAIT() asm volatile("s_waitcnt lgkmcnt(0)" ::: "memory")
; __device__ __forceinline__ void conv_fetch(const ConvJob& j, int lane, ConvSet& s) {
;     const int k0 = 64 * j.kb; int cnt; const int src = vgroup_src(j.kind, j.g, cnt);
;     const int ks = lane >> 3, n4 = (lane & 7) * 4, c = lane & 7; const bool okc = n4 < cnt;
;     const float* gp = j.gain ? j.gain + k0 + 8 * c : j.W;
;     s.g0 = *(const f32x4*)gp; s.g1 = *(const f32x4*)(gp + 4);
;     const float* wp = j.W + (size_t)(k0 + ks) * j.Norig + src + (okc ? n4 : 0);
; #pragma unroll
;     for (int i = 0; i < 8; ++i) s.v[i] = *(const f32x4*)(wp + (size_t)(8 * i) * j.Norig);
; }
; __device__ __forceinline__ void conv_emit(const ConvJob& j, int lane, const ConvSet& s, LAS float* scr) {
;     const int k0 = 64 * j.kb; int cnt; (void)vgroup_src(j.kind, j.g, cnt);
;     const int ks = lane >> 3, n4 = (lane & 7) * 4, c = lane & 7; const bool okc = n4 < cnt;
;     const f32x4 one = (f32x4){1.f, 1.f, 1.f, 1.f}; const f32x4 g0 = j.gain ? s.g0 : one, g1 = j.gain ? s.g1 : one;
; #pragma unroll
;     for (int i = 0; i < 8; ++i) { LAS float* sp = scr + (8 * i + ks) * 33 + n4;
; #pragma unroll
;         for (int e = 0; e < 4; ++e) sp[e] = okc ? s.v[i][e] : 0.f; }
;     LDS_WAIT(); asm volatile("" ::: "memory");
; #pragma unroll
;     for (int q = 0; q < 4; ++q) { const int nn = (lane >> 3) + 8 * q; const LAS float* sr = scr + (8 * c) * 33 + nn;
;         u32x4 o; o.x = cvtpk(sr[0 * 33] * g0[0], sr[1 * 33] * g0[1]); o.y = cvtpk(sr[2 * 33] * g0[2], sr[3 * 33] * g0[3]); o.z = cvtpk(sr[4 * 33] * g1[0], sr[5 * 33] * g1[1]); o.w = cvtpk(sr[6 * 33] * g1[2], sr[7 * 33] * g1[3]);
;         *(u32x4*)(j.WT + (size_t)(j.g * 32 + nn) * j.K + k0 + 8 * c) = o; }
.LBB0_1695:
	s_add_i32 s19, s18, s19
	s_min_i32 s19, s19, 0x57f
	s_ashr_i32 s22, s19, 31
	s_lshr_b32 s22, s22, 27
	s_add_i32 s22, s19, s22
	s_and_b32 s23, s22, 0x7ffffe0
	s_lshl_b32 s22, s22, 1
	s_sub_i32 s19, s19, s23
	s_and_b32 s23, s22, 0xffffffc0
	s_waitcnt vmcnt(27)
	v_or_b32_e32 v34, s23, v102
	v_ashrrev_i32_e32 v35, 31, v34
	s_lshl_b32 s22, s19, 5
	v_lshlrev_b64 v[34:35], 12, v[34:35]
	v_lshl_add_u64 v[34:35], s[46:47], 0, v[34:35]
	s_ashr_i32 s23, s22, 31
	v_lshl_add_u64 v[34:35], s[22:23], 2, v[34:35]
	s_waitcnt vmcnt(21)
	v_lshl_add_u64 v[58:59], v[34:35], 0, v[98:99]
	v_add_co_u32_e32 v38, vcc, s4, v58
	s_nop 1
	v_addc_co_u32_e32 v39, vcc, 0, v59, vcc
	v_add_co_u32_e32 v42, vcc, s5, v58
	global_load_dwordx4 v[34:37], v[58:59], off
	s_nop 0
	global_load_dwordx4 v[38:41], v[38:39], off
	v_addc_co_u32_e32 v43, vcc, 0, v59, vcc
	v_add_co_u32_e32 v46, vcc, s6, v58
	s_nop 1
	v_addc_co_u32_e32 v47, vcc, 0, v59, vcc
	v_add_co_u32_e32 v50, vcc, s7, v58
	global_load_dwordx4 v[42:45], v[42:43], off
	s_nop 0
	global_load_dwordx4 v[46:49], v[46:47], off
	v_addc_co_u32_e32 v51, vcc, 0, v59, vcc
	v_add_co_u32_e32 v54, vcc, 0x28000, v58
	s_nop 1
	v_addc_co_u32_e32 v55, vcc, 0, v59, vcc
	v_add_co_u32_e32 v60, vcc, 0x30000, v58
	global_load_dwordx4 v[50:53], v[50:51], off
	s_nop 0
	global_load_dwordx4 v[54:57], v[54:55], off
	v_addc_co_u32_e32 v61, vcc, 0, v59, vcc
	s_waitcnt vmcnt(26)
	v_add_co_u32_e32 v62, vcc, 0x38000, v58
	s_nop 1
	v_addc_co_u32_e32 v63, vcc, 0, v59, vcc
	global_load_dwordx4 v[58:61], v[60:61], off
	s_nop 0
	global_load_dwordx4 v[62:65], v[62:63], off
	s_andn2_b64 vcc, exec, s[0:1]
	s_cbranch_vccnz .LBB0_1692
	s_ashr_i32 s0, s20, 31
	s_lshr_b32 s0, s0, 27
	s_add_i32 s0, s20, s0
	s_waitcnt vmcnt(27)
	ds_write2_b32 v108, v66, v67 offset1:1
	ds_write2_b32 v108, v68, v69 offset0:2 offset1:3
	s_waitcnt vmcnt(26)
	ds_write2_b32 v109, v70, v71 offset1:1
	ds_write2_b32 v110, v72, v73 offset1:1
	s_waitcnt vmcnt(25)
	ds_write2_b32 v111, v74, v75 offset1:1
	ds_write2_b32 v112, v76, v77 offset1:1
	s_waitcnt vmcnt(24)
	ds_write2_b32 v113, v78, v79 offset1:1
	ds_write2_b32 v114, v80, v81 offset1:1
	s_waitcnt vmcnt(23)
	ds_write2_b32 v115, v82, v83 offset1:1
	ds_write2_b32 v116, v84, v85 offset1:1
	s_waitcnt vmcnt(22)
	ds_write2_b32 v117, v86, v87 offset1:1
	ds_write2_b32 v118, v88, v89 offset1:1
	s_waitcnt vmcnt(21)
	ds_write2_b32 v119, v94, v95 offset1:1
	ds_write2_b32 v120, v96, v97 offset1:1
	s_waitcnt vmcnt(20)
	ds_write2_b32 v121, v90, v91 offset1:1
	ds_write2_b32 v122, v92, v93 offset1:1
	s_and_b32 s1, s0, 0x7ffffe0
	s_waitcnt lgkmcnt(0)
	s_sub_i32 s19, s20, s1
	ds_read2_b32 v[70:71], v106 offset0:33 offset1:41
	ds_read2_b32 v[72:73], v106 offset1:8
	ds_read2_b32 v[74:75], v106 offset0:66 offset1:74
	ds_read2_b32 v[76:77], v106 offset0:99 offset1:107
	ds_read2_b32 v[78:79], v106 offset0:132 offset1:140
	ds_read2_b32 v[80:81], v106 offset0:165 offset1:173
	ds_read2_b32 v[82:83], v106 offset0:198 offset1:206
	ds_read2_b32 v[84:85], v106 offset0:231 offset1:239
	s_lshl_b32 s19, s19, 5
	s_lshl_b32 s0, s0, 1
	s_waitcnt lgkmcnt(6)
	v_cvt_pk_bf16_f32 v66, v72, v70
	v_or_b32_e32 v70, s19, v102
	s_andn2_b32 s0, s0, 63
	v_mul_lo_u32 v86, v70, s15
	s_ashr_i32 s1, s0, 31
	v_ashrrev_i32_e32 v87, 31, v86
	v_lshl_add_u64 v[86:87], s[78:79], 0, v[86:87]
	s_lshl_b64 s[0:1], s[0:1], 1
	v_lshl_add_u64 v[86:87], v[86:87], 0, s[0:1]
	v_mov_b32_e32 v101, v99
	v_or_b32_e32 v70, s19, v103
	s_waitcnt lgkmcnt(4)
	v_cvt_pk_bf16_f32 v67, v74, v76
	s_waitcnt lgkmcnt(2)
	v_cvt_pk_bf16_f32 v68, v78, v80
	s_waitcnt lgkmcnt(0)
	v_cvt_pk_bf16_f32 v69, v82, v84
	v_lshl_add_u64 v[86:87], v[86:87], 0, v[100:101]
	v_mul_lo_u32 v70, v70, s15
	global_store_dwordx4 v[86:87], v[66:69], off sc1
	s_nop 1
	v_cvt_pk_bf16_f32 v66, v73, v71
	v_ashrrev_i32_e32 v71, 31, v70
	v_lshl_add_u64 v[70:71], s[78:79], 0, v[70:71]
	v_lshl_add_u64 v[70:71], v[70:71], 0, s[0:1]
	v_cvt_pk_bf16_f32 v67, v75, v77
	v_cvt_pk_bf16_f32 v68, v79, v81
	v_cvt_pk_bf16_f32 v69, v83, v85
	v_lshl_add_u64 v[70:71], v[70:71], 0, v[100:101]
	ds_read2_b32 v[72:73], v106 offset0:49 offset1:57
	ds_read2_b32 v[74:75], v106 offset0:16 offset1:24
	ds_read2_b32 v[76:77], v106 offset0:82 offset1:90
	ds_read2_b32 v[78:79], v106 offset0:115 offset1:123
	ds_read2_b32 v[80:81], v106 offset0:148 offset1:156
	ds_read2_b32 v[82:83], v106 offset0:181 offset1:189
	ds_read2_b32 v[84:85], v106 offset0:214 offset1:222
	ds_read2_b32 v[86:87], v106 offset0:247 offset1:255
	global_store_dwordx4 v[70:71], v[66:69], off sc1
	v_or_b32_e32 v70, s19, v104
	v_mul_lo_u32 v70, v70, s15
	v_ashrrev_i32_e32 v71, 31, v70
	v_lshl_add_u64 v[70:71], s[78:79], 0, v[70:71]
	v_lshl_add_u64 v[70:71], v[70:71], 0, s[0:1]
	s_waitcnt lgkmcnt(6)
	v_cvt_pk_bf16_f32 v66, v74, v72
	s_waitcnt lgkmcnt(4)
	v_cvt_pk_bf16_f32 v67, v76, v78
	s_waitcnt lgkmcnt(2)
	v_cvt_pk_bf16_f32 v68, v80, v82
	s_waitcnt lgkmcnt(0)
	v_cvt_pk_bf16_f32 v69, v84, v86
	v_lshl_add_u64 v[70:71], v[70:71], 0, v[100:101]
	global_store_dwordx4 v[70:71], v[66:69], off sc1
	v_or_b32_e32 v70, s19, v105
	v_mul_lo_u32 v70, v70, s15
	v_ashrrev_i32_e32 v71, 31, v70
	v_lshl_add_u64 v[70:71], s[78:79], 0, v[70:71]
	v_lshl_add_u64 v[70:71], v[70:71], 0, s[0:1]
	v_cvt_pk_bf16_f32 v66, v75, v73
	v_cvt_pk_bf16_f32 v67, v77, v79
	v_cvt_pk_bf16_f32 v68, v81, v83
	v_cvt_pk_bf16_f32 v69, v85, v87
	v_lshl_add_u64 v[70:71], v[70:71], 0, v[100:101]
	global_store_dwordx4 v[70:71], v[66:69], off sc1
	s_waitcnt lgkmcnt(0)
	s_branch .LBB0_1692
